# write-through (sc1) stores for the bf16 operand copies (ob in P2/P11 epilogues, MB in P10b)
# speedup vs baseline: 1.0024x; 1.0015x over previous
; #define EPI_ROWS(...) _Pragma("unroll") for (int ai = 0; ai < 2; ++ai) _Pragma("unroll") for (int m = 0; m < 4; ++m) { const int row = row0 + ai * 128 + m * 16; __VA_ARGS__ __builtin_amdgcn_sched_barrier(0); }
; __device__ __forceinline__ u32x4 pack8(f32x4 a, f32x4 b) { u32x4 w; w.x = pk2(a[0], a[1]); w.y = pk2(a[2], a[3]); w.z = pk2(b[0], b[1]); w.w = pk2(b[2], b[3]); return w; }
; __device__ __forceinline__ float dot8(f32x4 a, f32x4 b) { return (a[0] * a[0] + a[1] * a[1]) + (a[2] * a[2] + a[3] * a[3]) + (b[0] * b[0] + b[1] * b[1]) + (b[2] * b[2] + b[3] * b[3]); }
; __device__ __forceinline__ float red_fq(float s) { s += __shfl_xor(s, 16); s += __shfl_xor(s, 32); return s; }
;     __device__ __forceinline__ void operator()(AccRef acc, const Unit& u, int wr, int wc, int fr, int fq) const {
;         const int row0 = u.pm * 256 + wr * 64 + fr, col0 = u.pn * 256 + wc * 32 + 8 * fq;
;         EPI_ROWS(
;             const float* rp = (row < MP) ? res0 + (size_t)row * DM : res1 + (size_t)(row - MP) * DM;
;             float s = 0.f;
;             _Pragma("unroll") for (int bj = 0; bj < 2; ++bj) { const int col = col0 + bj * 128;
;                 f32x4 v0 = *(const f32x4*)(rp + col) + acc[ai][bj][m][0] * scale, v1 = *(const f32x4*)(rp + col + 4) + acc[ai][bj][m][1] * scale;
;                 *(f32x4*)(out + (size_t)row * DM + col) = v0; *(f32x4*)(out + (size_t)row * DM + col + 4) = v1;
;                 if (WB) *(u32x4*)(ob + (size_t)row * DM + col) = pack8(v0, v1);
;                 s += dot8(v0, v1); }
;             s = red_fq(s); if (fq == 0) unsafeAtomicAdd(ss + row, s);
;         )
.LBB0_312:
	v_lshl_add_u32 v144, s96, 8, v155
	v_cmp_lt_i32_e32 vcc, s91, v144
	s_and_saveexec_b64 s[16:17], vcc
	s_xor_b64 s[16:17], exec, s[16:17]
	v_add_u32_e32 v138, 0xffff8000, v144
	v_mov_b32_e32 v139, v2
	v_lshlrev_b64 v[138:139], 12, v[138:139]
	v_lshl_add_u64 v[148:149], s[38:39], 0, v[138:139]
	v_mov_b32_e32 v145, v2
	s_andn2_saveexec_b64 s[16:17], s[16:17]
	v_ashrrev_i32_e32 v145, 31, v144
	v_lshlrev_b64 v[138:139], 12, v[144:145]
	v_lshl_add_u64 v[148:149], s[36:37], 0, v[138:139]
	s_or_b64 exec, exec, s[16:17]
	v_and_b32_e32 v138, 64, v193
	v_lshl_or_b32 v142, s95, 8, v188
	v_xor_b32_e32 v3, 16, v193
	v_add_u32_e32 v138, 64, v138
	v_cmp_lt_i32_e32 vcc, v3, v138
	v_ashrrev_i32_e32 v143, 31, v142
	v_lshlrev_b64 v[146:147], 2, v[142:143]
	v_cndmask_b32_e32 v3, v193, v3, vcc
	v_lshlrev_b32_e32 v195, 2, v3
	v_xor_b32_e32 v3, 32, v193
	v_lshl_add_u64 v[148:149], v[148:149], 0, v[146:147]
	v_cmp_lt_i32_e32 vcc, v3, v138
	global_load_dwordx4 v[138:141], v[148:149], off offset:16
	global_load_dwordx4 v[196:199], v[148:149], off
	global_load_dwordx4 v[216:219], v[148:149], off offset:528
	global_load_dwordx4 v[220:223], v[148:149], off offset:512
	v_cndmask_b32_e32 v3, v193, v3, vcc
	v_lshlrev_b32_e32 v3, 2, v3
	s_waitcnt vmcnt(3)
	v_pk_fma_f32 v[140:141], v[126:127], 0.5, v[140:141] op_sel_hi:[1,0,1]
	v_lshlrev_b64 v[126:127], 11, v[144:145]
	s_waitcnt vmcnt(2)
	v_pk_fma_f32 v[130:131], v[130:131], 0.5, v[198:199] op_sel_hi:[1,0,1]
	v_pk_fma_f32 v[128:129], v[128:129], 0.5, v[196:197] op_sel_hi:[1,0,1]
	v_lshl_add_u64 v[126:127], s[18:19], 0, v[126:127]
	v_lshl_add_u64 v[200:201], v[142:143], 1, v[126:127]
	v_mul_f32_e32 v126, v129, v129
	v_mul_f32_e32 v127, v131, v131
	v_pk_fma_f32 v[138:139], v[124:125], 0.5, v[138:139] op_sel_hi:[1,0,1]
	v_fmac_f32_e32 v126, v128, v128
	v_fmac_f32_e32 v127, v130, v130
	v_lshlrev_b64 v[124:125], 12, v[144:145]
	v_add_f32_e32 v126, v126, v127
	v_mul_f32_e32 v127, v139, v139
	v_lshl_add_u64 v[124:125], s[30:31], 0, v[124:125]
	v_fmac_f32_e32 v127, v138, v138
	v_lshl_add_u64 v[124:125], v[124:125], 0, v[146:147]
	v_cvt_pk_bf16_f32 v196, v128, v129
	v_cvt_pk_bf16_f32 v197, v130, v131
	v_cvt_pk_bf16_f32 v198, v138, v139
	v_cvt_pk_bf16_f32 v199, v140, v141
	v_add_f32_e32 v126, v127, v126
	v_mul_f32_e32 v127, v141, v141
	global_store_dwordx4 v[124:125], v[128:131], off
	global_store_dwordx4 v[124:125], v[138:141], off offset:16
	global_store_dwordx4 v[200:201], v[196:199], off sc1
	v_fmac_f32_e32 v127, v140, v140
	v_add_f32_e32 v130, v127, v126
	s_nop 0
	s_nop 0
	s_waitcnt vmcnt(4)
	v_pk_fma_f32 v[118:119], v[118:119], 0.5, v[218:219] op_sel_hi:[1,0,1]
	s_waitcnt vmcnt(3)
	v_pk_fma_f32 v[122:123], v[122:123], 0.5, v[222:223] op_sel_hi:[1,0,1]
	v_pk_fma_f32 v[120:121], v[120:121], 0.5, v[220:221] op_sel_hi:[1,0,1]
	v_pk_fma_f32 v[116:117], v[116:117], 0.5, v[216:217] op_sel_hi:[1,0,1]
	global_store_dwordx4 v[124:125], v[120:123], off offset:512
	global_store_dwordx4 v[124:125], v[116:119], off offset:528
	v_cvt_pk_bf16_f32 v124, v120, v121
	v_mul_f32_e32 v121, v121, v121
	v_fmac_f32_e32 v121, v120, v120
	v_mul_f32_e32 v120, v123, v123
	v_cvt_pk_bf16_f32 v126, v116, v117
	v_fmac_f32_e32 v120, v122, v122
	v_mul_f32_e32 v117, v117, v117
	v_add_f32_e32 v120, v121, v120
	v_fmac_f32_e32 v117, v116, v116
	v_add_f32_e32 v116, v117, v120
	v_mul_f32_e32 v117, v119, v119
	v_fmac_f32_e32 v117, v118, v118
	v_add_f32_e32 v116, v117, v116
	v_add_f32_e32 v116, v130, v116
	ds_bpermute_b32 v117, v195, v116
	v_cvt_pk_bf16_f32 v125, v122, v123
	v_cvt_pk_bf16_f32 v127, v118, v119
	global_store_dwordx4 v[200:201], v[124:127], off offset:256 sc1
	s_waitcnt lgkmcnt(0)
	v_add_f32_e32 v116, v116, v117
	ds_bpermute_b32 v117, v3, v116
	s_and_saveexec_b64 s[16:17], s[6:7]
	s_cbranch_execz .LBB0_318
	s_waitcnt lgkmcnt(0)
	v_add_f32_e32 v118, v116, v117
	v_lshl_add_u64 v[116:117], v[144:145], 2, s[84:85]
	v_mov_b32_e32 v224, v116
	v_mov_b32_e32 v225, v117
	v_mov_b32_e32 v226, v118
.LBB0_318:
	s_or_b64 exec, exec, s[16:17]
	s_waitcnt lgkmcnt(0)
	v_or_b32_e32 v116, 16, v144
	v_cmp_lt_i32_e32 vcc, s91, v116
	s_and_saveexec_b64 s[16:17], vcc
	s_xor_b64 s[16:17], exec, s[16:17]
	v_add_u32_e32 v118, 0xffff8010, v144
	v_mov_b32_e32 v119, v2
	v_lshlrev_b64 v[118:119], 12, v[118:119]
	v_lshl_add_u64 v[118:119], s[38:39], 0, v[118:119]
	v_mov_b32_e32 v117, v2
	s_andn2_saveexec_b64 s[16:17], s[16:17]
	v_ashrrev_i32_e32 v117, 31, v116
	v_lshlrev_b64 v[118:119], 12, v[116:117]
	v_lshl_add_u64 v[118:119], s[36:37], 0, v[118:119]
	s_or_b64 exec, exec, s[16:17]
	v_lshl_add_u64 v[126:127], v[118:119], 0, v[146:147]
	global_load_dwordx4 v[118:121], v[126:127], off offset:16
	global_load_dwordx4 v[122:125], v[126:127], off
	global_load_dwordx4 v[216:219], v[126:127], off offset:528
	global_load_dwordx4 v[220:223], v[126:127], off offset:512
	s_waitcnt vmcnt(3)
	v_pk_fma_f32 v[108:109], v[108:109], 0.5, v[118:119] op_sel_hi:[1,0,1]
	v_lshlrev_b64 v[118:119], 12, v[116:117]
	v_lshl_add_u64 v[118:119], s[30:31], 0, v[118:119]
	s_waitcnt vmcnt(2)
	v_pk_fma_f32 v[114:115], v[114:115], 0.5, v[124:125] op_sel_hi:[1,0,1]
	v_pk_fma_f32 v[112:113], v[112:113], 0.5, v[122:123] op_sel_hi:[1,0,1]
	v_lshl_add_u64 v[122:123], v[118:119], 0, v[146:147]
	v_pk_fma_f32 v[110:111], v[110:111], 0.5, v[120:121] op_sel_hi:[1,0,1]
	global_store_dwordx4 v[122:123], v[112:115], off
	global_store_dwordx4 v[122:123], v[108:111], off offset:16
	v_cvt_pk_bf16_f32 v118, v112, v113
	v_mul_f32_e32 v113, v113, v113
	v_fmac_f32_e32 v113, v112, v112
	v_mul_f32_e32 v112, v115, v115
	v_cvt_pk_bf16_f32 v120, v108, v109
	v_lshlrev_b64 v[124:125], 11, v[116:117]
	v_fmac_f32_e32 v112, v114, v114
	v_mul_f32_e32 v109, v109, v109
	v_lshl_add_u64 v[124:125], s[18:19], 0, v[124:125]
	v_add_f32_e32 v112, v113, v112
	v_fmac_f32_e32 v109, v108, v108
	v_cvt_pk_bf16_f32 v119, v114, v115
	v_cvt_pk_bf16_f32 v121, v110, v111
	v_lshl_add_u64 v[124:125], v[142:143], 1, v[124:125]
	v_add_f32_e32 v108, v109, v112
	v_mul_f32_e32 v109, v111, v111
	global_store_dwordx4 v[124:125], v[118:121], off sc1
	v_fmac_f32_e32 v109, v110, v110
	s_nop 0
	v_add_f32_e32 v118, v109, v108
	s_nop 0
	s_nop 0
	s_waitcnt vmcnt(4)
; #define EPI_ROWS(...) _Pragma("unroll") for (int ai = 0; ai < 2; ++ai) _Pragma("unroll") for (int m = 0; m < 4; ++m) { const int row = row0 + ai * 128 + m * 16; __VA_ARGS__ __builtin_amdgcn_sched_barrier(0); }
; __device__ __forceinline__ u32x4 pack8(f32x4 a, f32x4 b) { u32x4 w; w.x = pk2(a[0], a[1]); w.y = pk2(a[2], a[3]); w.z = pk2(b[0], b[1]); w.w = pk2(b[2], b[3]); return w; }
; __device__ __forceinline__ float dot8(f32x4 a, f32x4 b) { return (a[0] * a[0] + a[1] * a[1]) + (a[2] * a[2] + a[3] * a[3]) + (b[0] * b[0] + b[1] * b[1]) + (b[2] * b[2] + b[3] * b[3]); }
; __device__ __forceinline__ float red_fq(float s) { s += __shfl_xor(s, 16); s += __shfl_xor(s, 32); return s; }
;     __device__ __forceinline__ void operator()(AccRef acc, const Unit& u, int wr, int wc, int fr, int fq) const {
;         const int row0 = u.pm * 256 + wr * 64 + fr, col0 = u.pn * 256 + wc * 32 + 8 * fq;
;         EPI_ROWS(
;             const float* rp = (row < MP) ? res0 + (size_t)row * DM : res1 + (size_t)(row - MP) * DM;
;             float s = 0.f;
;             _Pragma("unroll") for (int bj = 0; bj < 2; ++bj) { const int col = col0 + bj * 128;
;                 f32x4 v0 = *(const f32x4*)(rp + col) + acc[ai][bj][m][0] * scale, v1 = *(const f32x4*)(rp + col + 4) + acc[ai][bj][m][1] * scale;
;                 *(f32x4*)(out + (size_t)row * DM + col) = v0; *(f32x4*)(out + (size_t)row * DM + col + 4) = v1;
;                 if (WB) *(u32x4*)(ob + (size_t)row * DM + col) = pack8(v0, v1);
;                 s += dot8(v0, v1); }
;             s = red_fq(s); if (fq == 0) unsafeAtomicAdd(ss + row, s);
;         )
	v_pk_fma_f32 v[102:103], v[102:103], 0.5, v[218:219] op_sel_hi:[1,0,1]
	s_waitcnt vmcnt(3)
	v_pk_fma_f32 v[106:107], v[106:107], 0.5, v[222:223] op_sel_hi:[1,0,1]
	v_pk_fma_f32 v[104:105], v[104:105], 0.5, v[220:221] op_sel_hi:[1,0,1]
	v_pk_fma_f32 v[100:101], v[100:101], 0.5, v[216:217] op_sel_hi:[1,0,1]
	global_store_dwordx4 v[122:123], v[104:107], off offset:512
	global_store_dwordx4 v[122:123], v[100:103], off offset:528
	v_cvt_pk_bf16_f32 v108, v104, v105
	v_mul_f32_e32 v105, v105, v105
	v_fmac_f32_e32 v105, v104, v104
	v_mul_f32_e32 v104, v107, v107
	v_cvt_pk_bf16_f32 v110, v100, v101
	v_fmac_f32_e32 v104, v106, v106
	v_mul_f32_e32 v101, v101, v101
	v_add_f32_e32 v104, v105, v104
	v_fmac_f32_e32 v101, v100, v100
	v_add_f32_e32 v100, v101, v104
	v_mul_f32_e32 v101, v103, v103
	v_fmac_f32_e32 v101, v102, v102
	v_add_f32_e32 v100, v101, v100
	v_add_f32_e32 v100, v118, v100
	ds_bpermute_b32 v101, v195, v100
	v_cvt_pk_bf16_f32 v109, v106, v107
	v_cvt_pk_bf16_f32 v111, v102, v103
	global_store_dwordx4 v[124:125], v[108:111], off offset:256 sc1
	s_waitcnt lgkmcnt(0)
	v_add_f32_e32 v100, v100, v101
	ds_bpermute_b32 v101, v3, v100
	s_and_saveexec_b64 s[16:17], s[6:7]
	s_cbranch_execz .LBB0_324
	s_waitcnt lgkmcnt(0)
	v_add_f32_e32 v102, v100, v101
	v_lshl_add_u64 v[100:101], v[116:117], 2, s[84:85]
	v_mov_b32_e32 v228, v100
	v_mov_b32_e32 v229, v101
	v_mov_b32_e32 v230, v102
.LBB0_324:
	s_or_b64 exec, exec, s[16:17]
	s_waitcnt lgkmcnt(0)
	v_or_b32_e32 v100, 32, v144
	v_cmp_lt_i32_e32 vcc, s91, v100
	s_and_saveexec_b64 s[16:17], vcc
	s_xor_b64 s[16:17], exec, s[16:17]
	v_add_u32_e32 v102, 0xffff8020, v144
	v_mov_b32_e32 v103, v2
	v_lshlrev_b64 v[102:103], 12, v[102:103]
	v_lshl_add_u64 v[102:103], s[38:39], 0, v[102:103]
	v_mov_b32_e32 v101, v2
	s_andn2_saveexec_b64 s[16:17], s[16:17]
	v_ashrrev_i32_e32 v101, 31, v100
	v_lshlrev_b64 v[102:103], 12, v[100:101]
	v_lshl_add_u64 v[102:103], s[36:37], 0, v[102:103]
	s_or_b64 exec, exec, s[16:17]
	v_lshl_add_u64 v[110:111], v[102:103], 0, v[146:147]
	global_load_dwordx4 v[102:105], v[110:111], off offset:16
	global_load_dwordx4 v[106:109], v[110:111], off
	global_load_dwordx4 v[216:219], v[110:111], off offset:528
	global_load_dwordx4 v[220:223], v[110:111], off offset:512
	s_waitcnt vmcnt(3)
	v_pk_fma_f32 v[92:93], v[92:93], 0.5, v[102:103] op_sel_hi:[1,0,1]
	v_lshlrev_b64 v[102:103], 12, v[100:101]
	v_lshl_add_u64 v[102:103], s[30:31], 0, v[102:103]
	s_waitcnt vmcnt(2)
	v_pk_fma_f32 v[98:99], v[98:99], 0.5, v[108:109] op_sel_hi:[1,0,1]
	v_pk_fma_f32 v[96:97], v[96:97], 0.5, v[106:107] op_sel_hi:[1,0,1]
	v_lshl_add_u64 v[106:107], v[102:103], 0, v[146:147]
	v_pk_fma_f32 v[94:95], v[94:95], 0.5, v[104:105] op_sel_hi:[1,0,1]
	global_store_dwordx4 v[106:107], v[96:99], off
	global_store_dwordx4 v[106:107], v[92:95], off offset:16
	v_cvt_pk_bf16_f32 v102, v96, v97
	v_mul_f32_e32 v97, v97, v97
	v_fmac_f32_e32 v97, v96, v96
	v_mul_f32_e32 v96, v99, v99
	v_cvt_pk_bf16_f32 v104, v92, v93
	v_lshlrev_b64 v[108:109], 11, v[100:101]
	v_fmac_f32_e32 v96, v98, v98
	v_mul_f32_e32 v93, v93, v93
	v_lshl_add_u64 v[108:109], s[18:19], 0, v[108:109]
	v_add_f32_e32 v96, v97, v96
	v_fmac_f32_e32 v93, v92, v92
	v_cvt_pk_bf16_f32 v103, v98, v99
	v_cvt_pk_bf16_f32 v105, v94, v95
	v_lshl_add_u64 v[108:109], v[142:143], 1, v[108:109]
	v_add_f32_e32 v92, v93, v96
	v_mul_f32_e32 v93, v95, v95
	global_store_dwordx4 v[108:109], v[102:105], off sc1
	v_fmac_f32_e32 v93, v94, v94
	s_nop 0
	v_add_f32_e32 v102, v93, v92
	s_nop 0
	s_nop 0
	s_waitcnt vmcnt(4)
	v_pk_fma_f32 v[86:87], v[86:87], 0.5, v[218:219] op_sel_hi:[1,0,1]
	s_waitcnt vmcnt(3)
	v_pk_fma_f32 v[90:91], v[90:91], 0.5, v[222:223] op_sel_hi:[1,0,1]
	v_pk_fma_f32 v[88:89], v[88:89], 0.5, v[220:221] op_sel_hi:[1,0,1]
	v_pk_fma_f32 v[84:85], v[84:85], 0.5, v[216:217] op_sel_hi:[1,0,1]
	global_store_dwordx4 v[106:107], v[88:91], off offset:512
	global_store_dwordx4 v[106:107], v[84:87], off offset:528
	v_cvt_pk_bf16_f32 v92, v88, v89
	v_mul_f32_e32 v89, v89, v89
	v_fmac_f32_e32 v89, v88, v88
	v_mul_f32_e32 v88, v91, v91
	v_cvt_pk_bf16_f32 v94, v84, v85
	v_fmac_f32_e32 v88, v90, v90
	v_mul_f32_e32 v85, v85, v85
	v_add_f32_e32 v88, v89, v88
	v_fmac_f32_e32 v85, v84, v84
	v_add_f32_e32 v84, v85, v88
	v_mul_f32_e32 v85, v87, v87
	v_fmac_f32_e32 v85, v86, v86
	v_add_f32_e32 v84, v85, v84
	v_add_f32_e32 v84, v102, v84
	ds_bpermute_b32 v85, v195, v84
	v_cvt_pk_bf16_f32 v93, v90, v91
	v_cvt_pk_bf16_f32 v95, v86, v87
	global_store_dwordx4 v[108:109], v[92:95], off offset:256 sc1
	s_waitcnt lgkmcnt(0)
	v_add_f32_e32 v84, v84, v85
	ds_bpermute_b32 v85, v3, v84
	s_and_saveexec_b64 s[16:17], s[6:7]
	s_cbranch_execz .LBB0_330
	s_waitcnt lgkmcnt(0)
	v_add_f32_e32 v86, v84, v85
	v_lshl_add_u64 v[84:85], v[100:101], 2, s[84:85]
	v_mov_b32_e32 v232, v84
	v_mov_b32_e32 v233, v85
	v_mov_b32_e32 v234, v86
; #define EPI_ROWS(...) _Pragma("unroll") for (int ai = 0; ai < 2; ++ai) _Pragma("unroll") for (int m = 0; m < 4; ++m) { const int row = row0 + ai * 128 + m * 16; __VA_ARGS__ __builtin_amdgcn_sched_barrier(0); }
; __device__ __forceinline__ u32x4 pack8(f32x4 a, f32x4 b) { u32x4 w; w.x = pk2(a[0], a[1]); w.y = pk2(a[2], a[3]); w.z = pk2(b[0], b[1]); w.w = pk2(b[2], b[3]); return w; }
; __device__ __forceinline__ float dot8(f32x4 a, f32x4 b) { return (a[0] * a[0] + a[1] * a[1]) + (a[2] * a[2] + a[3] * a[3]) + (b[0] * b[0] + b[1] * b[1]) + (b[2] * b[2] + b[3] * b[3]); }
; __device__ __forceinline__ float red_fq(float s) { s += __shfl_xor(s, 16); s += __shfl_xor(s, 32); return s; }
;     __device__ __forceinline__ void operator()(AccRef acc, const Unit& u, int wr, int wc, int fr, int fq) const {
;         const int row0 = u.pm * 256 + wr * 64 + fr, col0 = u.pn * 256 + wc * 32 + 8 * fq;
;         EPI_ROWS(
;             const float* rp = (row < MP) ? res0 + (size_t)row * DM : res1 + (size_t)(row - MP) * DM;
;             float s = 0.f;
;             _Pragma("unroll") for (int bj = 0; bj < 2; ++bj) { const int col = col0 + bj * 128;
;                 f32x4 v0 = *(const f32x4*)(rp + col) + acc[ai][bj][m][0] * scale, v1 = *(const f32x4*)(rp + col + 4) + acc[ai][bj][m][1] * scale;
;                 *(f32x4*)(out + (size_t)row * DM + col) = v0; *(f32x4*)(out + (size_t)row * DM + col + 4) = v1;
;                 if (WB) *(u32x4*)(ob + (size_t)row * DM + col) = pack8(v0, v1);
;                 s += dot8(v0, v1); }
;             s = red_fq(s); if (fq == 0) unsafeAtomicAdd(ss + row, s);
;         )
.LBB0_330:
	s_or_b64 exec, exec, s[16:17]
	s_waitcnt lgkmcnt(0)
	v_or_b32_e32 v84, 48, v144
	v_cmp_lt_i32_e32 vcc, s91, v84
	s_and_saveexec_b64 s[16:17], vcc
	s_xor_b64 s[16:17], exec, s[16:17]
	v_add_u32_e32 v86, 0xffff8030, v144
	v_mov_b32_e32 v87, v2
	v_lshlrev_b64 v[86:87], 12, v[86:87]
	v_lshl_add_u64 v[86:87], s[38:39], 0, v[86:87]
	v_mov_b32_e32 v85, v2
	s_andn2_saveexec_b64 s[16:17], s[16:17]
	v_ashrrev_i32_e32 v85, 31, v84
	v_lshlrev_b64 v[86:87], 12, v[84:85]
	v_lshl_add_u64 v[86:87], s[36:37], 0, v[86:87]
	s_or_b64 exec, exec, s[16:17]
	v_lshl_add_u64 v[94:95], v[86:87], 0, v[146:147]
	global_load_dwordx4 v[86:89], v[94:95], off offset:16
	global_load_dwordx4 v[90:93], v[94:95], off
	global_load_dwordx4 v[216:219], v[94:95], off offset:528
	global_load_dwordx4 v[220:223], v[94:95], off offset:512
	s_waitcnt vmcnt(3)
	v_pk_fma_f32 v[76:77], v[76:77], 0.5, v[86:87] op_sel_hi:[1,0,1]
	v_lshlrev_b64 v[86:87], 12, v[84:85]
	v_lshl_add_u64 v[86:87], s[30:31], 0, v[86:87]
	s_waitcnt vmcnt(2)
	v_pk_fma_f32 v[82:83], v[82:83], 0.5, v[92:93] op_sel_hi:[1,0,1]
	v_pk_fma_f32 v[80:81], v[80:81], 0.5, v[90:91] op_sel_hi:[1,0,1]
	v_lshl_add_u64 v[90:91], v[86:87], 0, v[146:147]
	v_pk_fma_f32 v[78:79], v[78:79], 0.5, v[88:89] op_sel_hi:[1,0,1]
	global_store_dwordx4 v[90:91], v[80:83], off
	global_store_dwordx4 v[90:91], v[76:79], off offset:16
	v_cvt_pk_bf16_f32 v86, v80, v81
	v_mul_f32_e32 v81, v81, v81
	v_fmac_f32_e32 v81, v80, v80
	v_mul_f32_e32 v80, v83, v83
	v_cvt_pk_bf16_f32 v88, v76, v77
	v_lshlrev_b64 v[92:93], 11, v[84:85]
	v_fmac_f32_e32 v80, v82, v82
	v_mul_f32_e32 v77, v77, v77
	v_lshl_add_u64 v[92:93], s[18:19], 0, v[92:93]
	v_add_f32_e32 v80, v81, v80
	v_fmac_f32_e32 v77, v76, v76
	v_cvt_pk_bf16_f32 v87, v82, v83
	v_cvt_pk_bf16_f32 v89, v78, v79
	v_lshl_add_u64 v[92:93], v[142:143], 1, v[92:93]
	v_add_f32_e32 v76, v77, v80
	v_mul_f32_e32 v77, v79, v79
	global_store_dwordx4 v[92:93], v[86:89], off sc1
	v_fmac_f32_e32 v77, v78, v78
	s_nop 0
	v_add_f32_e32 v86, v77, v76
	s_nop 0
	s_nop 0
	s_waitcnt vmcnt(4)
	v_pk_fma_f32 v[70:71], v[70:71], 0.5, v[218:219] op_sel_hi:[1,0,1]
	s_waitcnt vmcnt(3)
	v_pk_fma_f32 v[74:75], v[74:75], 0.5, v[222:223] op_sel_hi:[1,0,1]
	v_pk_fma_f32 v[72:73], v[72:73], 0.5, v[220:221] op_sel_hi:[1,0,1]
	v_pk_fma_f32 v[68:69], v[68:69], 0.5, v[216:217] op_sel_hi:[1,0,1]
	global_store_dwordx4 v[90:91], v[72:75], off offset:512
	global_store_dwordx4 v[90:91], v[68:71], off offset:528
	v_cvt_pk_bf16_f32 v76, v72, v73
	v_mul_f32_e32 v73, v73, v73
	v_fmac_f32_e32 v73, v72, v72
	v_mul_f32_e32 v72, v75, v75
	v_cvt_pk_bf16_f32 v78, v68, v69
	v_fmac_f32_e32 v72, v74, v74
	v_mul_f32_e32 v69, v69, v69
	v_add_f32_e32 v72, v73, v72
	v_fmac_f32_e32 v69, v68, v68
	v_add_f32_e32 v68, v69, v72
	v_mul_f32_e32 v69, v71, v71
	v_fmac_f32_e32 v69, v70, v70
	v_add_f32_e32 v68, v69, v68
	v_add_f32_e32 v68, v86, v68
	ds_bpermute_b32 v69, v195, v68
	v_cvt_pk_bf16_f32 v77, v74, v75
	v_cvt_pk_bf16_f32 v79, v70, v71
	global_store_dwordx4 v[92:93], v[76:79], off offset:256 sc1
	s_waitcnt lgkmcnt(0)
	v_add_f32_e32 v68, v68, v69
	ds_bpermute_b32 v69, v3, v68
	s_and_saveexec_b64 s[16:17], s[6:7]
	s_cbranch_execz .LBB0_336
	s_waitcnt lgkmcnt(0)
	v_add_f32_e32 v70, v68, v69
	v_lshl_add_u64 v[68:69], v[84:85], 2, s[84:85]
	v_mov_b32_e32 v236, v68
	v_mov_b32_e32 v237, v69
	v_mov_b32_e32 v238, v70
.LBB0_336:
	s_or_b64 exec, exec, s[16:17]
	s_movk_i32 s10, 0x7f7f
	s_waitcnt lgkmcnt(0)
	v_add_u32_e32 v68, 0x80, v144
	v_cmp_lt_i32_e32 vcc, s10, v144
	s_and_saveexec_b64 s[16:17], vcc
	s_xor_b64 s[16:17], exec, s[16:17]
	v_add_u32_e32 v70, 0xffff8080, v144
	v_mov_b32_e32 v71, v2
	v_lshlrev_b64 v[70:71], 12, v[70:71]
	v_lshl_add_u64 v[70:71], s[38:39], 0, v[70:71]
	v_mov_b32_e32 v69, v2
	s_andn2_saveexec_b64 s[16:17], s[16:17]
	v_ashrrev_i32_e32 v69, 31, v68
	v_lshlrev_b64 v[70:71], 12, v[68:69]
	v_lshl_add_u64 v[70:71], s[36:37], 0, v[70:71]
	s_or_b64 exec, exec, s[16:17]
	v_lshl_add_u64 v[78:79], v[70:71], 0, v[146:147]
	global_load_dwordx4 v[70:73], v[78:79], off offset:16
	global_load_dwordx4 v[74:77], v[78:79], off
	global_load_dwordx4 v[216:219], v[78:79], off offset:528
	global_load_dwordx4 v[220:223], v[78:79], off offset:512
	s_waitcnt vmcnt(3)
	v_pk_fma_f32 v[60:61], v[60:61], 0.5, v[70:71] op_sel_hi:[1,0,1]
	v_lshlrev_b64 v[70:71], 12, v[68:69]
	v_lshl_add_u64 v[70:71], s[30:31], 0, v[70:71]
	s_waitcnt vmcnt(2)
	v_pk_fma_f32 v[66:67], v[66:67], 0.5, v[76:77] op_sel_hi:[1,0,1]
	v_pk_fma_f32 v[64:65], v[64:65], 0.5, v[74:75] op_sel_hi:[1,0,1]
	v_lshl_add_u64 v[74:75], v[70:71], 0, v[146:147]
	v_pk_fma_f32 v[62:63], v[62:63], 0.5, v[72:73] op_sel_hi:[1,0,1]
	global_store_dwordx4 v[74:75], v[64:67], off
	global_store_dwordx4 v[74:75], v[60:63], off offset:16
	v_cvt_pk_bf16_f32 v70, v64, v65
	v_mul_f32_e32 v65, v65, v65
	v_fmac_f32_e32 v65, v64, v64
	v_mul_f32_e32 v64, v67, v67
	v_cvt_pk_bf16_f32 v72, v60, v61
	v_lshlrev_b64 v[76:77], 11, v[68:69]
	v_fmac_f32_e32 v64, v66, v66
	v_mul_f32_e32 v61, v61, v61
	v_lshl_add_u64 v[76:77], s[18:19], 0, v[76:77]
	v_add_f32_e32 v64, v65, v64
	v_fmac_f32_e32 v61, v60, v60
	v_cvt_pk_bf16_f32 v71, v66, v67
	v_cvt_pk_bf16_f32 v73, v62, v63
	v_lshl_add_u64 v[76:77], v[142:143], 1, v[76:77]
	v_add_f32_e32 v60, v61, v64
	v_mul_f32_e32 v61, v63, v63
	global_store_dwordx4 v[76:77], v[70:73], off sc1
	v_fmac_f32_e32 v61, v62, v62
	s_nop 0
	v_add_f32_e32 v70, v61, v60
	s_nop 0
	s_nop 0
	s_waitcnt vmcnt(4)
	v_pk_fma_f32 v[54:55], v[54:55], 0.5, v[218:219] op_sel_hi:[1,0,1]
	s_waitcnt vmcnt(3)
	v_pk_fma_f32 v[58:59], v[58:59], 0.5, v[222:223] op_sel_hi:[1,0,1]
	v_pk_fma_f32 v[56:57], v[56:57], 0.5, v[220:221] op_sel_hi:[1,0,1]
	v_pk_fma_f32 v[52:53], v[52:53], 0.5, v[216:217] op_sel_hi:[1,0,1]
	global_store_dwordx4 v[74:75], v[56:59], off offset:512
	global_store_dwordx4 v[74:75], v[52:55], off offset:528
	v_cvt_pk_bf16_f32 v60, v56, v57
	v_mul_f32_e32 v57, v57, v57
	v_fmac_f32_e32 v57, v56, v56
	v_mul_f32_e32 v56, v59, v59
	v_cvt_pk_bf16_f32 v62, v52, v53
	v_fmac_f32_e32 v56, v58, v58
	v_mul_f32_e32 v53, v53, v53
	v_add_f32_e32 v56, v57, v56
	v_fmac_f32_e32 v53, v52, v52
	v_add_f32_e32 v52, v53, v56
	v_mul_f32_e32 v53, v55, v55
	v_fmac_f32_e32 v53, v54, v54
	v_add_f32_e32 v52, v53, v52
	v_add_f32_e32 v52, v70, v52
	ds_bpermute_b32 v53, v195, v52
	v_cvt_pk_bf16_f32 v61, v58, v59
	v_cvt_pk_bf16_f32 v63, v54, v55
	global_store_dwordx4 v[76:77], v[60:63], off offset:256 sc1
	s_waitcnt lgkmcnt(0)
	v_add_f32_e32 v52, v52, v53
	ds_bpermute_b32 v53, v3, v52
	s_and_saveexec_b64 s[16:17], s[6:7]
	s_cbranch_execz .LBB0_342
	s_waitcnt lgkmcnt(0)
	v_add_f32_e32 v54, v52, v53
	v_lshl_add_u64 v[52:53], v[68:69], 2, s[84:85]
	v_mov_b32_e32 v240, v52
	v_mov_b32_e32 v241, v53
	v_mov_b32_e32 v242, v54
; #define EPI_ROWS(...) _Pragma("unroll") for (int ai = 0; ai < 2; ++ai) _Pragma("unroll") for (int m = 0; m < 4; ++m) { const int row = row0 + ai * 128 + m * 16; __VA_ARGS__ __builtin_amdgcn_sched_barrier(0); }
; __device__ __forceinline__ u32x4 pack8(f32x4 a, f32x4 b) { u32x4 w; w.x = pk2(a[0], a[1]); w.y = pk2(a[2], a[3]); w.z = pk2(b[0], b[1]); w.w = pk2(b[2], b[3]); return w; }
; __device__ __forceinline__ float dot8(f32x4 a, f32x4 b) { return (a[0] * a[0] + a[1] * a[1]) + (a[2] * a[2] + a[3] * a[3]) + (b[0] * b[0] + b[1] * b[1]) + (b[2] * b[2] + b[3] * b[3]); }
; __device__ __forceinline__ float red_fq(float s) { s += __shfl_xor(s, 16); s += __shfl_xor(s, 32); return s; }
;     __device__ __forceinline__ void operator()(AccRef acc, const Unit& u, int wr, int wc, int fr, int fq) const {
;         const int row0 = u.pm * 256 + wr * 64 + fr, col0 = u.pn * 256 + wc * 32 + 8 * fq;
;         EPI_ROWS(
;             const float* rp = (row < MP) ? res0 + (size_t)row * DM : res1 + (size_t)(row - MP) * DM;
;             float s = 0.f;
;             _Pragma("unroll") for (int bj = 0; bj < 2; ++bj) { const int col = col0 + bj * 128;
;                 f32x4 v0 = *(const f32x4*)(rp + col) + acc[ai][bj][m][0] * scale, v1 = *(const f32x4*)(rp + col + 4) + acc[ai][bj][m][1] * scale;
;                 *(f32x4*)(out + (size_t)row * DM + col) = v0; *(f32x4*)(out + (size_t)row * DM + col + 4) = v1;
;                 if (WB) *(u32x4*)(ob + (size_t)row * DM + col) = pack8(v0, v1);
;                 s += dot8(v0, v1); }
;             s = red_fq(s); if (fq == 0) unsafeAtomicAdd(ss + row, s);
;         )
.LBB0_342:
	s_or_b64 exec, exec, s[16:17]
	s_movk_i32 s10, 0x7f6f
	s_waitcnt lgkmcnt(0)
	v_add_u32_e32 v52, 0x90, v144
	v_cmp_lt_i32_e32 vcc, s10, v144
	s_and_saveexec_b64 s[16:17], vcc
	s_xor_b64 s[16:17], exec, s[16:17]
	v_add_u32_e32 v54, 0xffff8090, v144
	v_mov_b32_e32 v55, v2
	v_lshlrev_b64 v[54:55], 12, v[54:55]
	v_lshl_add_u64 v[54:55], s[38:39], 0, v[54:55]
	v_mov_b32_e32 v53, v2
	s_andn2_saveexec_b64 s[16:17], s[16:17]
	v_ashrrev_i32_e32 v53, 31, v52
	v_lshlrev_b64 v[54:55], 12, v[52:53]
	v_lshl_add_u64 v[54:55], s[36:37], 0, v[54:55]
	s_or_b64 exec, exec, s[16:17]
	v_lshl_add_u64 v[62:63], v[54:55], 0, v[146:147]
	global_load_dwordx4 v[54:57], v[62:63], off offset:16
	global_load_dwordx4 v[58:61], v[62:63], off
	global_load_dwordx4 v[216:219], v[62:63], off offset:528
	global_load_dwordx4 v[220:223], v[62:63], off offset:512
	s_waitcnt vmcnt(3)
	v_pk_fma_f32 v[44:45], v[44:45], 0.5, v[54:55] op_sel_hi:[1,0,1]
	v_lshlrev_b64 v[54:55], 12, v[52:53]
	v_lshl_add_u64 v[54:55], s[30:31], 0, v[54:55]
	s_waitcnt vmcnt(2)
	v_pk_fma_f32 v[50:51], v[50:51], 0.5, v[60:61] op_sel_hi:[1,0,1]
	v_pk_fma_f32 v[48:49], v[48:49], 0.5, v[58:59] op_sel_hi:[1,0,1]
	v_lshl_add_u64 v[58:59], v[54:55], 0, v[146:147]
	v_pk_fma_f32 v[46:47], v[46:47], 0.5, v[56:57] op_sel_hi:[1,0,1]
	global_store_dwordx4 v[58:59], v[48:51], off
	global_store_dwordx4 v[58:59], v[44:47], off offset:16
	v_cvt_pk_bf16_f32 v54, v48, v49
	v_mul_f32_e32 v49, v49, v49
	v_fmac_f32_e32 v49, v48, v48
	v_mul_f32_e32 v48, v51, v51
	v_cvt_pk_bf16_f32 v56, v44, v45
	v_lshlrev_b64 v[60:61], 11, v[52:53]
	v_fmac_f32_e32 v48, v50, v50
	v_mul_f32_e32 v45, v45, v45
	v_lshl_add_u64 v[60:61], s[18:19], 0, v[60:61]
	v_add_f32_e32 v48, v49, v48
	v_fmac_f32_e32 v45, v44, v44
	v_cvt_pk_bf16_f32 v55, v50, v51
	v_cvt_pk_bf16_f32 v57, v46, v47
	v_lshl_add_u64 v[60:61], v[142:143], 1, v[60:61]
	v_add_f32_e32 v44, v45, v48
	v_mul_f32_e32 v45, v47, v47
	global_store_dwordx4 v[60:61], v[54:57], off sc1
	v_fmac_f32_e32 v45, v46, v46
	s_nop 0
	v_add_f32_e32 v54, v45, v44
	s_nop 0
	s_nop 0
	s_waitcnt vmcnt(4)
	v_pk_fma_f32 v[38:39], v[38:39], 0.5, v[218:219] op_sel_hi:[1,0,1]
	s_waitcnt vmcnt(3)
	v_pk_fma_f32 v[42:43], v[42:43], 0.5, v[222:223] op_sel_hi:[1,0,1]
	v_pk_fma_f32 v[40:41], v[40:41], 0.5, v[220:221] op_sel_hi:[1,0,1]
	v_pk_fma_f32 v[36:37], v[36:37], 0.5, v[216:217] op_sel_hi:[1,0,1]
	global_store_dwordx4 v[58:59], v[40:43], off offset:512
	global_store_dwordx4 v[58:59], v[36:39], off offset:528
	v_cvt_pk_bf16_f32 v44, v40, v41
	v_mul_f32_e32 v41, v41, v41
	v_fmac_f32_e32 v41, v40, v40
	v_mul_f32_e32 v40, v43, v43
	v_cvt_pk_bf16_f32 v46, v36, v37
	v_fmac_f32_e32 v40, v42, v42
	v_mul_f32_e32 v37, v37, v37
	v_add_f32_e32 v40, v41, v40
	v_fmac_f32_e32 v37, v36, v36
	v_add_f32_e32 v36, v37, v40
	v_mul_f32_e32 v37, v39, v39
	v_fmac_f32_e32 v37, v38, v38
	v_add_f32_e32 v36, v37, v36
	v_add_f32_e32 v36, v54, v36
	ds_bpermute_b32 v37, v195, v36
	v_cvt_pk_bf16_f32 v45, v42, v43
	v_cvt_pk_bf16_f32 v47, v38, v39
	global_store_dwordx4 v[60:61], v[44:47], off offset:256 sc1
	s_waitcnt lgkmcnt(0)
	v_add_f32_e32 v36, v36, v37
	ds_bpermute_b32 v37, v3, v36
	s_and_saveexec_b64 s[16:17], s[6:7]
	s_cbranch_execz .LBB0_348
	s_waitcnt lgkmcnt(0)
	v_add_f32_e32 v38, v36, v37
	v_lshl_add_u64 v[36:37], v[52:53], 2, s[84:85]
	v_mov_b32_e32 v244, v36
	v_mov_b32_e32 v245, v37
	v_mov_b32_e32 v246, v38
.LBB0_348:
	s_or_b64 exec, exec, s[16:17]
	s_movk_i32 s10, 0x7f5f
	s_waitcnt lgkmcnt(0)
	v_add_u32_e32 v36, 0xa0, v144
	v_cmp_lt_i32_e32 vcc, s10, v144
	s_and_saveexec_b64 s[16:17], vcc
	s_xor_b64 s[16:17], exec, s[16:17]
	v_add_u32_e32 v38, 0xffff80a0, v144
	v_mov_b32_e32 v39, v2
	v_lshlrev_b64 v[38:39], 12, v[38:39]
	v_lshl_add_u64 v[38:39], s[38:39], 0, v[38:39]
	v_mov_b32_e32 v37, v2
	s_andn2_saveexec_b64 s[16:17], s[16:17]
	v_ashrrev_i32_e32 v37, 31, v36
	v_lshlrev_b64 v[38:39], 12, v[36:37]
	v_lshl_add_u64 v[38:39], s[36:37], 0, v[38:39]
	s_or_b64 exec, exec, s[16:17]
	v_lshl_add_u64 v[46:47], v[38:39], 0, v[146:147]
	global_load_dwordx4 v[38:41], v[46:47], off offset:16
	global_load_dwordx4 v[42:45], v[46:47], off
	global_load_dwordx4 v[216:219], v[46:47], off offset:528
	global_load_dwordx4 v[220:223], v[46:47], off offset:512
	s_waitcnt vmcnt(3)
	v_pk_fma_f32 v[28:29], v[28:29], 0.5, v[38:39] op_sel_hi:[1,0,1]
	v_lshlrev_b64 v[38:39], 12, v[36:37]
	v_lshl_add_u64 v[38:39], s[30:31], 0, v[38:39]
	s_waitcnt vmcnt(2)
	v_pk_fma_f32 v[34:35], v[34:35], 0.5, v[44:45] op_sel_hi:[1,0,1]
	v_pk_fma_f32 v[32:33], v[32:33], 0.5, v[42:43] op_sel_hi:[1,0,1]
	v_lshl_add_u64 v[42:43], v[38:39], 0, v[146:147]
	v_pk_fma_f32 v[30:31], v[30:31], 0.5, v[40:41] op_sel_hi:[1,0,1]
	global_store_dwordx4 v[42:43], v[32:35], off
	global_store_dwordx4 v[42:43], v[28:31], off offset:16
	v_cvt_pk_bf16_f32 v38, v32, v33
	v_mul_f32_e32 v33, v33, v33
	v_fmac_f32_e32 v33, v32, v32
	v_mul_f32_e32 v32, v35, v35
	v_cvt_pk_bf16_f32 v40, v28, v29
	v_lshlrev_b64 v[44:45], 11, v[36:37]
	v_fmac_f32_e32 v32, v34, v34
	v_mul_f32_e32 v29, v29, v29
	v_lshl_add_u64 v[44:45], s[18:19], 0, v[44:45]
	v_add_f32_e32 v32, v33, v32
	v_fmac_f32_e32 v29, v28, v28
	v_cvt_pk_bf16_f32 v39, v34, v35
	v_cvt_pk_bf16_f32 v41, v30, v31
	v_lshl_add_u64 v[44:45], v[142:143], 1, v[44:45]
	v_add_f32_e32 v28, v29, v32
	v_mul_f32_e32 v29, v31, v31
	global_store_dwordx4 v[44:45], v[38:41], off sc1
	v_fmac_f32_e32 v29, v30, v30
	s_nop 0
	v_add_f32_e32 v38, v29, v28
	s_nop 0
	s_nop 0
	s_waitcnt vmcnt(4)
	v_pk_fma_f32 v[22:23], v[22:23], 0.5, v[218:219] op_sel_hi:[1,0,1]
	s_waitcnt vmcnt(3)
	v_pk_fma_f32 v[26:27], v[26:27], 0.5, v[222:223] op_sel_hi:[1,0,1]
	v_pk_fma_f32 v[24:25], v[24:25], 0.5, v[220:221] op_sel_hi:[1,0,1]
	v_pk_fma_f32 v[20:21], v[20:21], 0.5, v[216:217] op_sel_hi:[1,0,1]
	global_store_dwordx4 v[42:43], v[24:27], off offset:512
	global_store_dwordx4 v[42:43], v[20:23], off offset:528
	v_cvt_pk_bf16_f32 v28, v24, v25
	v_mul_f32_e32 v25, v25, v25
	v_fmac_f32_e32 v25, v24, v24
	v_mul_f32_e32 v24, v27, v27
	v_cvt_pk_bf16_f32 v30, v20, v21
	v_fmac_f32_e32 v24, v26, v26
	v_mul_f32_e32 v21, v21, v21
	v_add_f32_e32 v24, v25, v24
	v_fmac_f32_e32 v21, v20, v20
	v_add_f32_e32 v20, v21, v24
	v_mul_f32_e32 v21, v23, v23
	v_fmac_f32_e32 v21, v22, v22
	v_add_f32_e32 v20, v21, v20
	v_add_f32_e32 v20, v38, v20
	ds_bpermute_b32 v21, v195, v20
	v_cvt_pk_bf16_f32 v29, v26, v27
	v_cvt_pk_bf16_f32 v31, v22, v23
	global_store_dwordx4 v[44:45], v[28:31], off offset:256 sc1
	s_waitcnt lgkmcnt(0)
	v_add_f32_e32 v20, v20, v21
	ds_bpermute_b32 v21, v3, v20
	s_and_saveexec_b64 s[16:17], s[6:7]
	s_cbranch_execz .LBB0_354
	s_waitcnt lgkmcnt(0)
	v_add_f32_e32 v22, v20, v21
	v_lshl_add_u64 v[20:21], v[36:37], 2, s[84:85]
	v_mov_b32_e32 v248, v20
	v_mov_b32_e32 v249, v21
	v_mov_b32_e32 v250, v22
; #define EPI_ROWS(...) _Pragma("unroll") for (int ai = 0; ai < 2; ++ai) _Pragma("unroll") for (int m = 0; m < 4; ++m) { const int row = row0 + ai * 128 + m * 16; __VA_ARGS__ __builtin_amdgcn_sched_barrier(0); }
; __device__ __forceinline__ u32x4 pack8(f32x4 a, f32x4 b) { u32x4 w; w.x = pk2(a[0], a[1]); w.y = pk2(a[2], a[3]); w.z = pk2(b[0], b[1]); w.w = pk2(b[2], b[3]); return w; }
; __device__ __forceinline__ float dot8(f32x4 a, f32x4 b) { return (a[0] * a[0] + a[1] * a[1]) + (a[2] * a[2] + a[3] * a[3]) + (b[0] * b[0] + b[1] * b[1]) + (b[2] * b[2] + b[3] * b[3]); }
; __device__ __forceinline__ float red_fq(float s) { s += __shfl_xor(s, 16); s += __shfl_xor(s, 32); return s; }
;     __device__ __forceinline__ void operator()(AccRef acc, const Unit& u, int wr, int wc, int fr, int fq) const {
;         const int row0 = u.pm * 256 + wr * 64 + fr, col0 = u.pn * 256 + wc * 32 + 8 * fq;
;         EPI_ROWS(
;             const float* rp = (row < MP) ? res0 + (size_t)row * DM : res1 + (size_t)(row - MP) * DM;
;             float s = 0.f;
;             _Pragma("unroll") for (int bj = 0; bj < 2; ++bj) { const int col = col0 + bj * 128;
;                 f32x4 v0 = *(const f32x4*)(rp + col) + acc[ai][bj][m][0] * scale, v1 = *(const f32x4*)(rp + col + 4) + acc[ai][bj][m][1] * scale;
;                 *(f32x4*)(out + (size_t)row * DM + col) = v0; *(f32x4*)(out + (size_t)row * DM + col + 4) = v1;
;                 if (WB) *(u32x4*)(ob + (size_t)row * DM + col) = pack8(v0, v1);
;                 s += dot8(v0, v1); }
;             s = red_fq(s); if (fq == 0) unsafeAtomicAdd(ss + row, s);
;         )
.LBB0_354:
	s_or_b64 exec, exec, s[16:17]
	s_movk_i32 s10, 0x7f4f
	s_waitcnt lgkmcnt(0)
	v_add_u32_e32 v20, 0xb0, v144
	v_cmp_lt_i32_e32 vcc, s10, v144
	s_and_saveexec_b64 s[16:17], vcc
	s_xor_b64 s[16:17], exec, s[16:17]
	v_add_u32_e32 v22, 0xffff80b0, v144
	v_mov_b32_e32 v23, v2
	v_lshlrev_b64 v[22:23], 12, v[22:23]
	v_lshl_add_u64 v[22:23], s[38:39], 0, v[22:23]
	v_mov_b32_e32 v21, v2
	s_andn2_saveexec_b64 s[16:17], s[16:17]
	v_ashrrev_i32_e32 v21, 31, v20
	v_lshlrev_b64 v[22:23], 12, v[20:21]
	v_lshl_add_u64 v[22:23], s[36:37], 0, v[22:23]
	s_or_b64 exec, exec, s[16:17]
	v_lshl_add_u64 v[30:31], v[22:23], 0, v[146:147]
	global_load_dwordx4 v[22:25], v[30:31], off offset:16
	global_load_dwordx4 v[26:29], v[30:31], off
	global_load_dwordx4 v[216:219], v[30:31], off offset:528
	global_load_dwordx4 v[220:223], v[30:31], off offset:512
	s_waitcnt vmcnt(3)
	v_pk_fma_f32 v[12:13], v[12:13], 0.5, v[22:23] op_sel_hi:[1,0,1]
	v_lshlrev_b64 v[22:23], 12, v[20:21]
	v_lshl_add_u64 v[22:23], s[30:31], 0, v[22:23]
	s_waitcnt vmcnt(2)
	v_pk_fma_f32 v[18:19], v[18:19], 0.5, v[28:29] op_sel_hi:[1,0,1]
	v_pk_fma_f32 v[16:17], v[16:17], 0.5, v[26:27] op_sel_hi:[1,0,1]
	v_lshl_add_u64 v[26:27], v[22:23], 0, v[146:147]
	v_pk_fma_f32 v[14:15], v[14:15], 0.5, v[24:25] op_sel_hi:[1,0,1]
	global_store_dwordx4 v[26:27], v[16:19], off
	global_store_dwordx4 v[26:27], v[12:15], off offset:16
	v_cvt_pk_bf16_f32 v22, v16, v17
	v_mul_f32_e32 v17, v17, v17
	v_fmac_f32_e32 v17, v16, v16
	v_mul_f32_e32 v16, v19, v19
	v_cvt_pk_bf16_f32 v24, v12, v13
	v_lshlrev_b64 v[28:29], 11, v[20:21]
	v_fmac_f32_e32 v16, v18, v18
	v_mul_f32_e32 v13, v13, v13
	v_lshl_add_u64 v[28:29], s[18:19], 0, v[28:29]
	v_add_f32_e32 v16, v17, v16
	v_fmac_f32_e32 v13, v12, v12
	v_cvt_pk_bf16_f32 v23, v18, v19
	v_cvt_pk_bf16_f32 v25, v14, v15
	v_lshl_add_u64 v[28:29], v[142:143], 1, v[28:29]
	v_add_f32_e32 v12, v13, v16
	v_mul_f32_e32 v13, v15, v15
	global_store_dwordx4 v[28:29], v[22:25], off sc1
	v_fmac_f32_e32 v13, v14, v14
	s_nop 0
	v_add_f32_e32 v22, v13, v12
	s_nop 0
	s_nop 0
	s_waitcnt vmcnt(4)
	v_pk_fma_f32 v[6:7], v[6:7], 0.5, v[218:219] op_sel_hi:[1,0,1]
	s_waitcnt vmcnt(3)
	v_pk_fma_f32 v[10:11], v[10:11], 0.5, v[222:223] op_sel_hi:[1,0,1]
	v_pk_fma_f32 v[8:9], v[8:9], 0.5, v[220:221] op_sel_hi:[1,0,1]
	v_pk_fma_f32 v[4:5], v[4:5], 0.5, v[216:217] op_sel_hi:[1,0,1]
	global_store_dwordx4 v[26:27], v[8:11], off offset:512
	global_store_dwordx4 v[26:27], v[4:7], off offset:528
	v_cvt_pk_bf16_f32 v12, v8, v9
	v_mul_f32_e32 v9, v9, v9
	v_fmac_f32_e32 v9, v8, v8
	v_mul_f32_e32 v8, v11, v11
	v_cvt_pk_bf16_f32 v14, v4, v5
	v_fmac_f32_e32 v8, v10, v10
	v_mul_f32_e32 v5, v5, v5
	v_add_f32_e32 v8, v9, v8
	v_fmac_f32_e32 v5, v4, v4
	v_add_f32_e32 v4, v5, v8
	v_mul_f32_e32 v5, v7, v7
	v_fmac_f32_e32 v5, v6, v6
	v_add_f32_e32 v4, v5, v4
	v_add_f32_e32 v4, v22, v4
	ds_bpermute_b32 v5, v195, v4
	v_cvt_pk_bf16_f32 v13, v10, v11
	v_cvt_pk_bf16_f32 v15, v6, v7
	global_store_dwordx4 v[28:29], v[12:15], off offset:256 sc1
	s_waitcnt lgkmcnt(0)
	v_add_f32_e32 v4, v4, v5
	ds_bpermute_b32 v3, v3, v4
	s_and_saveexec_b64 s[16:17], s[6:7]
	s_cbranch_execz .LBB0_360
	s_waitcnt lgkmcnt(0)
	v_add_f32_e32 v3, v4, v3
	v_lshl_add_u64 v[4:5], v[20:21], 2, s[84:85]
	global_atomic_add_f32 v[4:5], v3, off
	global_atomic_add_f32 v[224:225], v226, off
	global_atomic_add_f32 v[228:229], v230, off
	global_atomic_add_f32 v[232:233], v234, off
	global_atomic_add_f32 v[236:237], v238, off
	global_atomic_add_f32 v[240:241], v242, off
	global_atomic_add_f32 v[244:245], v246, off
	global_atomic_add_f32 v[248:249], v250, off

; __device__ __forceinline__ float bflo(unsigned w) { return __uint_as_float(w << 16); }
; __device__ __forceinline__ float bfhi(unsigned w) { return __uint_as_float(w & 0xffff0000u); }
; #define EPI_ROWS(...) _Pragma("unroll") for (int ai = 0; ai < 2; ++ai) _Pragma("unroll") for (int m = 0; m < 4; ++m) { const int row = row0 + ai * 128 + m * 16; __VA_ARGS__ __builtin_amdgcn_sched_barrier(0); }
; __device__ __forceinline__ u32x4 pack8(f32x4 a, f32x4 b) { u32x4 w; w.x = pk2(a[0], a[1]); w.y = pk2(a[2], a[3]); w.z = pk2(b[0], b[1]); w.w = pk2(b[2], b[3]); return w; }
;     __device__ __forceinline__ void operator()(AccRef acc, const Unit& u, int wr, int wc, int fr, int fq) const {
;         const int row0 = u.pm * 256 + wr * 64 + fr, col0 = u.pn * 256 + wc * 32 + 8 * fq;
;         EPI_ROWS(
;             _Pragma("unroll") for (int bj = 0; bj < 2; ++bj) { const int col = col0 + bj * 128;
;                 const u32x2 gw = *(const u32x2*)(ZG8 + (size_t)row * 2048 + WHICH * 1024 + col);
;                 f32x4 v[2];
;                 _Pragma("unroll") for (int n = 0; n < 2; ++n) _Pragma("unroll") for (int i = 0; i < 4; ++i) v[n][i] = acc[ai][bj][m][n][i] * ((float)((gw[n] >> (8 * i)) & 255u) * (1.f / 255.f));
;                 if (WHICH == 0) *(u32x4*)(M1 + (size_t)row * 1024 + col) = pack8(v[0], v[1]);
;                 else { const u32x4 mw = *(const u32x4*)(M1 + (size_t)row * 1024 + col);
;                     _Pragma("unroll") for (int n = 0; n < 2; ++n) { v[n][0] += bflo(mw[2 * n]); v[n][1] += bfhi(mw[2 * n]); v[n][2] += bflo(mw[2 * n + 1]); v[n][3] += bfhi(mw[2 * n + 1]); }
;                     *(u32x4*)(MB + (size_t)row * 1024 + col) = pack8(v[0], v[1]); } }
.LBB0_1294:
	v_lshl_add_u32 v142, s54, 8, v147
	v_ashrrev_i32_e32 v143, 31, v142
	v_lshl_or_b32 v136, s52, 8, v148
	v_lshlrev_b64 v[138:139], 11, v[142:143]
	v_lshl_add_u64 v[134:135], s[22:23], 0, v[138:139]
	v_ashrrev_i32_e32 v137, 31, v136
	v_lshl_add_u64 v[158:159], v[134:135], 0, v[136:137]
	v_lshl_add_u64 v[154:155], s[20:21], 0, v[138:139]
	v_lshlrev_b64 v[134:135], 1, v[136:137]
	global_load_dwordx2 v[160:161], v[158:159], off offset:1024
	v_lshl_add_u64 v[162:163], v[154:155], 0, v[134:135]
	global_load_dwordx4 v[154:157], v[162:163], off
	global_load_dwordx2 v[200:201], v[158:159], off offset:1152
	global_load_dwordx4 v[204:207], v[162:163], off offset:256
	v_lshl_add_u64 v[164:165], s[36:37], 0, v[138:139]
	v_lshl_add_u64 v[164:165], v[164:165], 0, v[134:135]
	s_waitcnt vmcnt(3)
	v_cvt_f32_ubyte1_e32 v167, v160
	v_cvt_f32_ubyte0_e32 v166, v160
	v_cvt_f32_ubyte3_e32 v171, v160
	v_cvt_f32_ubyte2_e32 v170, v160
	v_cvt_f32_ubyte1_e32 v173, v161
	v_cvt_f32_ubyte0_e32 v172, v161
	v_cvt_f32_ubyte3_e32 v177, v161
	v_cvt_f32_ubyte2_e32 v176, v161
	s_waitcnt vmcnt(2)
	v_lshlrev_b32_e32 v168, 16, v154
	v_and_b32_e32 v169, 0xffff0000, v154
	v_lshlrev_b32_e32 v154, 16, v155
	v_and_b32_e32 v155, 0xffff0000, v155
	v_lshlrev_b32_e32 v174, 16, v156
	v_and_b32_e32 v175, 0xffff0000, v156
	v_lshlrev_b32_e32 v156, 16, v157
	v_and_b32_e32 v157, 0xffff0000, v157
	v_pk_mul_f32 v[160:161], v[166:167], s[10:11] op_sel_hi:[1,0]
	v_pk_mul_f32 v[166:167], v[170:171], s[10:11] op_sel_hi:[1,0]
	v_pk_mul_f32 v[170:171], v[172:173], s[10:11] op_sel_hi:[1,0]
	v_pk_mul_f32 v[172:173], v[176:177], s[10:11] op_sel_hi:[1,0]
	v_pk_fma_f32 v[126:127], v[126:127], v[160:161], v[168:169]
	v_pk_fma_f32 v[128:129], v[128:129], v[166:167], v[154:155]
	v_pk_fma_f32 v[154:155], v[122:123], v[170:171], v[174:175]
	v_pk_fma_f32 v[156:157], v[124:125], v[172:173], v[156:157]
	v_cvt_pk_bf16_f32 v122, v126, v127
	v_cvt_pk_bf16_f32 v123, v128, v129
	v_cvt_pk_bf16_f32 v124, v154, v155
	v_cvt_pk_bf16_f32 v125, v156, v157
	global_store_dwordx4 v[164:165], v[122:125], off sc1
	s_nop 0
	s_nop 0
	s_nop 0
	s_waitcnt vmcnt(2)
	v_cvt_f32_ubyte1_e32 v129, v200
	v_cvt_f32_ubyte0_e32 v128, v200
	v_cvt_f32_ubyte3_e32 v157, v200
	v_cvt_f32_ubyte2_e32 v156, v200
	v_cvt_f32_ubyte1_e32 v159, v201
	v_cvt_f32_ubyte0_e32 v158, v201
	v_cvt_f32_ubyte3_e32 v163, v201
	v_cvt_f32_ubyte2_e32 v162, v201
	s_waitcnt vmcnt(1)
	v_lshlrev_b32_e32 v154, 16, v204
	v_and_b32_e32 v155, 0xffff0000, v204
	v_lshlrev_b32_e32 v122, 16, v205
	v_and_b32_e32 v123, 0xffff0000, v205
	v_lshlrev_b32_e32 v160, 16, v206
	v_and_b32_e32 v161, 0xffff0000, v206
	v_lshlrev_b32_e32 v124, 16, v207
	v_and_b32_e32 v125, 0xffff0000, v207
	v_pk_mul_f32 v[126:127], v[128:129], s[10:11] op_sel_hi:[1,0]
	v_pk_mul_f32 v[128:129], v[156:157], s[10:11] op_sel_hi:[1,0]
	v_pk_mul_f32 v[156:157], v[158:159], s[10:11] op_sel_hi:[1,0]
	v_pk_mul_f32 v[158:159], v[162:163], s[10:11] op_sel_hi:[1,0]
	v_pk_fma_f32 v[118:119], v[118:119], v[126:127], v[154:155]
	v_pk_fma_f32 v[120:121], v[120:121], v[128:129], v[122:123]
	v_pk_fma_f32 v[122:123], v[114:115], v[156:157], v[160:161]
	v_pk_fma_f32 v[124:125], v[116:117], v[158:159], v[124:125]
	v_cvt_pk_bf16_f32 v114, v118, v119
	v_cvt_pk_bf16_f32 v115, v120, v121
	v_cvt_pk_bf16_f32 v116, v122, v123
	v_cvt_pk_bf16_f32 v117, v124, v125
	global_store_dwordx4 v[164:165], v[114:117], off offset:256 sc1
	s_nop 1
	v_or_b32_e32 v114, 16, v142
	v_ashrrev_i32_e32 v115, 31, v114
	v_lshlrev_b64 v[118:119], 11, v[114:115]
	v_lshl_add_u64 v[114:115], s[22:23], 0, v[118:119]
	v_lshl_add_u64 v[120:121], v[114:115], 0, v[136:137]
	v_lshl_add_u64 v[114:115], s[20:21], 0, v[118:119]
	global_load_dwordx2 v[122:123], v[120:121], off offset:1024
	v_lshl_add_u64 v[124:125], v[114:115], 0, v[134:135]
	global_load_dwordx4 v[114:117], v[124:125], off
	global_load_dwordx2 v[200:201], v[120:121], off offset:1152
	global_load_dwordx4 v[204:207], v[124:125], off offset:256
	v_lshl_add_u64 v[118:119], s[36:37], 0, v[118:119]
	v_lshl_add_u64 v[118:119], v[118:119], 0, v[134:135]
	s_waitcnt vmcnt(3)
	v_cvt_f32_ubyte1_e32 v127, v122
	v_cvt_f32_ubyte0_e32 v126, v122
	v_cvt_f32_ubyte3_e32 v155, v122
	v_cvt_f32_ubyte2_e32 v154, v122
	v_cvt_f32_ubyte1_e32 v157, v123
	v_cvt_f32_ubyte0_e32 v156, v123
	v_cvt_f32_ubyte3_e32 v161, v123
	v_cvt_f32_ubyte2_e32 v160, v123
	s_waitcnt vmcnt(2)
	v_lshlrev_b32_e32 v128, 16, v114
	v_and_b32_e32 v129, 0xffff0000, v114
	v_lshlrev_b32_e32 v114, 16, v115
	v_and_b32_e32 v115, 0xffff0000, v115
	v_lshlrev_b32_e32 v158, 16, v116
	v_and_b32_e32 v159, 0xffff0000, v116
	v_lshlrev_b32_e32 v116, 16, v117
	v_and_b32_e32 v117, 0xffff0000, v117
	v_pk_mul_f32 v[122:123], v[126:127], s[10:11] op_sel_hi:[1,0]
	v_pk_mul_f32 v[126:127], v[154:155], s[10:11] op_sel_hi:[1,0]
	v_pk_mul_f32 v[154:155], v[156:157], s[10:11] op_sel_hi:[1,0]
	v_pk_mul_f32 v[156:157], v[160:161], s[10:11] op_sel_hi:[1,0]
	v_pk_fma_f32 v[110:111], v[110:111], v[122:123], v[128:129]
	v_pk_fma_f32 v[112:113], v[112:113], v[126:127], v[114:115]
	v_pk_fma_f32 v[114:115], v[106:107], v[154:155], v[158:159]
	v_pk_fma_f32 v[116:117], v[108:109], v[156:157], v[116:117]
	v_cvt_pk_bf16_f32 v106, v110, v111
	v_cvt_pk_bf16_f32 v107, v112, v113
	v_cvt_pk_bf16_f32 v108, v114, v115
	v_cvt_pk_bf16_f32 v109, v116, v117
	global_store_dwordx4 v[118:119], v[106:109], off sc1
	s_nop 0
	s_nop 0
	s_nop 0
	s_waitcnt vmcnt(2)
	v_cvt_f32_ubyte1_e32 v113, v200
	v_cvt_f32_ubyte0_e32 v112, v200
	v_cvt_f32_ubyte3_e32 v117, v200
	v_cvt_f32_ubyte2_e32 v116, v200
	v_cvt_f32_ubyte1_e32 v121, v201
	v_cvt_f32_ubyte0_e32 v120, v201
	v_cvt_f32_ubyte3_e32 v125, v201
	v_cvt_f32_ubyte2_e32 v124, v201
	s_waitcnt vmcnt(1)
; __device__ __forceinline__ float bflo(unsigned w) { return __uint_as_float(w << 16); }
; __device__ __forceinline__ float bfhi(unsigned w) { return __uint_as_float(w & 0xffff0000u); }
; #define EPI_ROWS(...) _Pragma("unroll") for (int ai = 0; ai < 2; ++ai) _Pragma("unroll") for (int m = 0; m < 4; ++m) { const int row = row0 + ai * 128 + m * 16; __VA_ARGS__ __builtin_amdgcn_sched_barrier(0); }
; __device__ __forceinline__ u32x4 pack8(f32x4 a, f32x4 b) { u32x4 w; w.x = pk2(a[0], a[1]); w.y = pk2(a[2], a[3]); w.z = pk2(b[0], b[1]); w.w = pk2(b[2], b[3]); return w; }
;     __device__ __forceinline__ void operator()(AccRef acc, const Unit& u, int wr, int wc, int fr, int fq) const {
;         const int row0 = u.pm * 256 + wr * 64 + fr, col0 = u.pn * 256 + wc * 32 + 8 * fq;
;         EPI_ROWS(
;             _Pragma("unroll") for (int bj = 0; bj < 2; ++bj) { const int col = col0 + bj * 128;
;                 const u32x2 gw = *(const u32x2*)(ZG8 + (size_t)row * 2048 + WHICH * 1024 + col);
;                 f32x4 v[2];
;                 _Pragma("unroll") for (int n = 0; n < 2; ++n) _Pragma("unroll") for (int i = 0; i < 4; ++i) v[n][i] = acc[ai][bj][m][n][i] * ((float)((gw[n] >> (8 * i)) & 255u) * (1.f / 255.f));
;                 if (WHICH == 0) *(u32x4*)(M1 + (size_t)row * 1024 + col) = pack8(v[0], v[1]);
;                 else { const u32x4 mw = *(const u32x4*)(M1 + (size_t)row * 1024 + col);
;                     _Pragma("unroll") for (int n = 0; n < 2; ++n) { v[n][0] += bflo(mw[2 * n]); v[n][1] += bfhi(mw[2 * n]); v[n][2] += bflo(mw[2 * n + 1]); v[n][3] += bfhi(mw[2 * n + 1]); }
;                     *(u32x4*)(MB + (size_t)row * 1024 + col) = pack8(v[0], v[1]); } }
	v_lshlrev_b32_e32 v114, 16, v204
	v_and_b32_e32 v115, 0xffff0000, v204
	v_lshlrev_b32_e32 v106, 16, v205
	v_and_b32_e32 v107, 0xffff0000, v205
	v_lshlrev_b32_e32 v122, 16, v206
	v_and_b32_e32 v123, 0xffff0000, v206
	v_lshlrev_b32_e32 v108, 16, v207
	v_and_b32_e32 v109, 0xffff0000, v207
	v_pk_mul_f32 v[110:111], v[112:113], s[10:11] op_sel_hi:[1,0]
	v_pk_mul_f32 v[112:113], v[116:117], s[10:11] op_sel_hi:[1,0]
	v_pk_mul_f32 v[116:117], v[120:121], s[10:11] op_sel_hi:[1,0]
	v_pk_mul_f32 v[120:121], v[124:125], s[10:11] op_sel_hi:[1,0]
	v_pk_fma_f32 v[102:103], v[102:103], v[110:111], v[114:115]
	v_pk_fma_f32 v[104:105], v[104:105], v[112:113], v[106:107]
	v_pk_fma_f32 v[106:107], v[98:99], v[116:117], v[122:123]
	v_pk_fma_f32 v[108:109], v[100:101], v[120:121], v[108:109]
	v_cvt_pk_bf16_f32 v98, v102, v103
	v_cvt_pk_bf16_f32 v99, v104, v105
	v_cvt_pk_bf16_f32 v100, v106, v107
	v_cvt_pk_bf16_f32 v101, v108, v109
	global_store_dwordx4 v[118:119], v[98:101], off offset:256 sc1
	s_nop 1
	v_or_b32_e32 v98, 32, v142
	v_ashrrev_i32_e32 v99, 31, v98
	v_lshlrev_b64 v[102:103], 11, v[98:99]
	v_lshl_add_u64 v[98:99], s[22:23], 0, v[102:103]
	v_lshl_add_u64 v[104:105], v[98:99], 0, v[136:137]
	v_lshl_add_u64 v[98:99], s[20:21], 0, v[102:103]
	global_load_dwordx2 v[106:107], v[104:105], off offset:1024
	v_lshl_add_u64 v[108:109], v[98:99], 0, v[134:135]
	global_load_dwordx4 v[98:101], v[108:109], off
	global_load_dwordx2 v[200:201], v[104:105], off offset:1152
	global_load_dwordx4 v[204:207], v[108:109], off offset:256
	v_lshl_add_u64 v[102:103], s[36:37], 0, v[102:103]
	v_lshl_add_u64 v[102:103], v[102:103], 0, v[134:135]
	s_waitcnt vmcnt(3)
	v_cvt_f32_ubyte1_e32 v111, v106
	v_cvt_f32_ubyte0_e32 v110, v106
	v_cvt_f32_ubyte3_e32 v115, v106
	v_cvt_f32_ubyte2_e32 v114, v106
	v_cvt_f32_ubyte1_e32 v117, v107
	v_cvt_f32_ubyte0_e32 v116, v107
	v_cvt_f32_ubyte3_e32 v121, v107
	v_cvt_f32_ubyte2_e32 v120, v107
	s_waitcnt vmcnt(2)
	v_lshlrev_b32_e32 v112, 16, v98
	v_and_b32_e32 v113, 0xffff0000, v98
	v_lshlrev_b32_e32 v98, 16, v99
	v_and_b32_e32 v99, 0xffff0000, v99
	v_lshlrev_b32_e32 v118, 16, v100
	v_and_b32_e32 v119, 0xffff0000, v100
	v_lshlrev_b32_e32 v100, 16, v101
	v_and_b32_e32 v101, 0xffff0000, v101
	v_pk_mul_f32 v[106:107], v[110:111], s[10:11] op_sel_hi:[1,0]
	v_pk_mul_f32 v[110:111], v[114:115], s[10:11] op_sel_hi:[1,0]
	v_pk_mul_f32 v[114:115], v[116:117], s[10:11] op_sel_hi:[1,0]
	v_pk_mul_f32 v[116:117], v[120:121], s[10:11] op_sel_hi:[1,0]
	v_pk_fma_f32 v[94:95], v[94:95], v[106:107], v[112:113]
	v_pk_fma_f32 v[96:97], v[96:97], v[110:111], v[98:99]
	v_pk_fma_f32 v[98:99], v[90:91], v[114:115], v[118:119]
	v_pk_fma_f32 v[100:101], v[92:93], v[116:117], v[100:101]
	v_cvt_pk_bf16_f32 v90, v94, v95
	v_cvt_pk_bf16_f32 v91, v96, v97
	v_cvt_pk_bf16_f32 v92, v98, v99
	v_cvt_pk_bf16_f32 v93, v100, v101
	global_store_dwordx4 v[102:103], v[90:93], off sc1
	s_nop 0
	s_nop 0
	s_nop 0
	s_waitcnt vmcnt(2)
	v_cvt_f32_ubyte1_e32 v97, v200
	v_cvt_f32_ubyte0_e32 v96, v200
	v_cvt_f32_ubyte3_e32 v101, v200
	v_cvt_f32_ubyte2_e32 v100, v200
	v_cvt_f32_ubyte1_e32 v105, v201
	v_cvt_f32_ubyte0_e32 v104, v201
	v_cvt_f32_ubyte3_e32 v109, v201
	v_cvt_f32_ubyte2_e32 v108, v201
	s_waitcnt vmcnt(1)
	v_lshlrev_b32_e32 v98, 16, v204
	v_and_b32_e32 v99, 0xffff0000, v204
	v_lshlrev_b32_e32 v90, 16, v205
	v_and_b32_e32 v91, 0xffff0000, v205
	v_lshlrev_b32_e32 v106, 16, v206
	v_and_b32_e32 v107, 0xffff0000, v206
	v_lshlrev_b32_e32 v92, 16, v207
	v_and_b32_e32 v93, 0xffff0000, v207
	v_pk_mul_f32 v[94:95], v[96:97], s[10:11] op_sel_hi:[1,0]
	v_pk_mul_f32 v[96:97], v[100:101], s[10:11] op_sel_hi:[1,0]
	v_pk_mul_f32 v[100:101], v[104:105], s[10:11] op_sel_hi:[1,0]
	v_pk_mul_f32 v[104:105], v[108:109], s[10:11] op_sel_hi:[1,0]
	v_pk_fma_f32 v[86:87], v[86:87], v[94:95], v[98:99]
	v_pk_fma_f32 v[88:89], v[88:89], v[96:97], v[90:91]
	v_pk_fma_f32 v[90:91], v[82:83], v[100:101], v[106:107]
	v_pk_fma_f32 v[92:93], v[84:85], v[104:105], v[92:93]
	v_cvt_pk_bf16_f32 v82, v86, v87
	v_cvt_pk_bf16_f32 v83, v88, v89
	v_cvt_pk_bf16_f32 v84, v90, v91
	v_cvt_pk_bf16_f32 v85, v92, v93
	global_store_dwordx4 v[102:103], v[82:85], off offset:256 sc1
	s_nop 1
	v_or_b32_e32 v82, 48, v142
	v_ashrrev_i32_e32 v83, 31, v82
	v_lshlrev_b64 v[86:87], 11, v[82:83]
	v_lshl_add_u64 v[82:83], s[22:23], 0, v[86:87]
	v_lshl_add_u64 v[88:89], v[82:83], 0, v[136:137]
	v_lshl_add_u64 v[82:83], s[20:21], 0, v[86:87]
	global_load_dwordx2 v[90:91], v[88:89], off offset:1024
	v_lshl_add_u64 v[92:93], v[82:83], 0, v[134:135]
	global_load_dwordx4 v[82:85], v[92:93], off
	global_load_dwordx2 v[200:201], v[88:89], off offset:1152
	global_load_dwordx4 v[204:207], v[92:93], off offset:256
	v_lshl_add_u64 v[86:87], s[36:37], 0, v[86:87]
	v_lshl_add_u64 v[86:87], v[86:87], 0, v[134:135]
	s_waitcnt vmcnt(3)
	v_cvt_f32_ubyte1_e32 v95, v90
	v_cvt_f32_ubyte0_e32 v94, v90
	v_cvt_f32_ubyte3_e32 v99, v90
	v_cvt_f32_ubyte2_e32 v98, v90
	v_cvt_f32_ubyte1_e32 v101, v91
	v_cvt_f32_ubyte0_e32 v100, v91
	v_cvt_f32_ubyte3_e32 v105, v91
	v_cvt_f32_ubyte2_e32 v104, v91
	s_waitcnt vmcnt(2)
	v_lshlrev_b32_e32 v96, 16, v82
	v_and_b32_e32 v97, 0xffff0000, v82
	v_lshlrev_b32_e32 v82, 16, v83
	v_and_b32_e32 v83, 0xffff0000, v83
	v_lshlrev_b32_e32 v102, 16, v84
	v_and_b32_e32 v103, 0xffff0000, v84
	v_lshlrev_b32_e32 v84, 16, v85
	v_and_b32_e32 v85, 0xffff0000, v85
	v_pk_mul_f32 v[90:91], v[94:95], s[10:11] op_sel_hi:[1,0]
	v_pk_mul_f32 v[94:95], v[98:99], s[10:11] op_sel_hi:[1,0]
	v_pk_mul_f32 v[98:99], v[100:101], s[10:11] op_sel_hi:[1,0]
	v_pk_mul_f32 v[100:101], v[104:105], s[10:11] op_sel_hi:[1,0]
	v_pk_fma_f32 v[78:79], v[78:79], v[90:91], v[96:97]
	v_pk_fma_f32 v[80:81], v[80:81], v[94:95], v[82:83]
	v_pk_fma_f32 v[82:83], v[74:75], v[98:99], v[102:103]
	v_pk_fma_f32 v[84:85], v[76:77], v[100:101], v[84:85]
	v_cvt_pk_bf16_f32 v74, v78, v79
	v_cvt_pk_bf16_f32 v75, v80, v81
	v_cvt_pk_bf16_f32 v76, v82, v83
	v_cvt_pk_bf16_f32 v77, v84, v85
	global_store_dwordx4 v[86:87], v[74:77], off sc1
	s_nop 0
	s_nop 0
	s_nop 0
	s_waitcnt vmcnt(2)
; __device__ __forceinline__ float bflo(unsigned w) { return __uint_as_float(w << 16); }
; __device__ __forceinline__ float bfhi(unsigned w) { return __uint_as_float(w & 0xffff0000u); }
; #define EPI_ROWS(...) _Pragma("unroll") for (int ai = 0; ai < 2; ++ai) _Pragma("unroll") for (int m = 0; m < 4; ++m) { const int row = row0 + ai * 128 + m * 16; __VA_ARGS__ __builtin_amdgcn_sched_barrier(0); }
; __device__ __forceinline__ u32x4 pack8(f32x4 a, f32x4 b) { u32x4 w; w.x = pk2(a[0], a[1]); w.y = pk2(a[2], a[3]); w.z = pk2(b[0], b[1]); w.w = pk2(b[2], b[3]); return w; }
;     __device__ __forceinline__ void operator()(AccRef acc, const Unit& u, int wr, int wc, int fr, int fq) const {
;         const int row0 = u.pm * 256 + wr * 64 + fr, col0 = u.pn * 256 + wc * 32 + 8 * fq;
;         EPI_ROWS(
;             _Pragma("unroll") for (int bj = 0; bj < 2; ++bj) { const int col = col0 + bj * 128;
;                 const u32x2 gw = *(const u32x2*)(ZG8 + (size_t)row * 2048 + WHICH * 1024 + col);
;                 f32x4 v[2];
;                 _Pragma("unroll") for (int n = 0; n < 2; ++n) _Pragma("unroll") for (int i = 0; i < 4; ++i) v[n][i] = acc[ai][bj][m][n][i] * ((float)((gw[n] >> (8 * i)) & 255u) * (1.f / 255.f));
;                 if (WHICH == 0) *(u32x4*)(M1 + (size_t)row * 1024 + col) = pack8(v[0], v[1]);
;                 else { const u32x4 mw = *(const u32x4*)(M1 + (size_t)row * 1024 + col);
;                     _Pragma("unroll") for (int n = 0; n < 2; ++n) { v[n][0] += bflo(mw[2 * n]); v[n][1] += bfhi(mw[2 * n]); v[n][2] += bflo(mw[2 * n + 1]); v[n][3] += bfhi(mw[2 * n + 1]); }
;                     *(u32x4*)(MB + (size_t)row * 1024 + col) = pack8(v[0], v[1]); } }
	v_cvt_f32_ubyte1_e32 v81, v200
	v_cvt_f32_ubyte0_e32 v80, v200
	v_cvt_f32_ubyte3_e32 v85, v200
	v_cvt_f32_ubyte2_e32 v84, v200
	v_cvt_f32_ubyte1_e32 v89, v201
	v_cvt_f32_ubyte0_e32 v88, v201
	v_cvt_f32_ubyte3_e32 v93, v201
	v_cvt_f32_ubyte2_e32 v92, v201
	s_waitcnt vmcnt(1)
	v_lshlrev_b32_e32 v82, 16, v204
	v_and_b32_e32 v83, 0xffff0000, v204
	v_lshlrev_b32_e32 v74, 16, v205
	v_and_b32_e32 v75, 0xffff0000, v205
	v_lshlrev_b32_e32 v90, 16, v206
	v_and_b32_e32 v91, 0xffff0000, v206
	v_lshlrev_b32_e32 v76, 16, v207
	v_and_b32_e32 v77, 0xffff0000, v207
	v_pk_mul_f32 v[78:79], v[80:81], s[10:11] op_sel_hi:[1,0]
	v_pk_mul_f32 v[80:81], v[84:85], s[10:11] op_sel_hi:[1,0]
	v_pk_mul_f32 v[84:85], v[88:89], s[10:11] op_sel_hi:[1,0]
	v_pk_mul_f32 v[88:89], v[92:93], s[10:11] op_sel_hi:[1,0]
	v_pk_fma_f32 v[70:71], v[70:71], v[78:79], v[82:83]
	v_pk_fma_f32 v[72:73], v[72:73], v[80:81], v[74:75]
	v_pk_fma_f32 v[74:75], v[66:67], v[84:85], v[90:91]
	v_pk_fma_f32 v[76:77], v[68:69], v[88:89], v[76:77]
	v_cvt_pk_bf16_f32 v66, v70, v71
	v_cvt_pk_bf16_f32 v67, v72, v73
	v_cvt_pk_bf16_f32 v68, v74, v75
	v_cvt_pk_bf16_f32 v69, v76, v77
	global_store_dwordx4 v[86:87], v[66:69], off offset:256 sc1
	v_lshl_add_u64 v[70:71], v[138:139], 0, s[0:1]
	s_nop 0
	v_lshl_add_u64 v[66:67], s[22:23], 0, v[70:71]
	v_lshl_add_u64 v[72:73], v[66:67], 0, v[136:137]
	v_lshl_add_u64 v[66:67], s[20:21], 0, v[70:71]
	global_load_dwordx2 v[74:75], v[72:73], off offset:1024
	v_lshl_add_u64 v[76:77], v[66:67], 0, v[134:135]
	global_load_dwordx4 v[66:69], v[76:77], off
	global_load_dwordx2 v[200:201], v[72:73], off offset:1152
	global_load_dwordx4 v[204:207], v[76:77], off offset:256
	v_lshl_add_u64 v[70:71], s[36:37], 0, v[70:71]
	v_lshl_add_u64 v[70:71], v[70:71], 0, v[134:135]
	s_waitcnt vmcnt(3)
	v_cvt_f32_ubyte1_e32 v79, v74
	v_cvt_f32_ubyte0_e32 v78, v74
	v_cvt_f32_ubyte3_e32 v83, v74
	v_cvt_f32_ubyte2_e32 v82, v74
	v_cvt_f32_ubyte1_e32 v85, v75
	v_cvt_f32_ubyte0_e32 v84, v75
	v_cvt_f32_ubyte3_e32 v89, v75
	v_cvt_f32_ubyte2_e32 v88, v75
	s_waitcnt vmcnt(2)
	v_lshlrev_b32_e32 v80, 16, v66
	v_and_b32_e32 v81, 0xffff0000, v66
	v_lshlrev_b32_e32 v66, 16, v67
	v_and_b32_e32 v67, 0xffff0000, v67
	v_lshlrev_b32_e32 v86, 16, v68
	v_and_b32_e32 v87, 0xffff0000, v68
	v_lshlrev_b32_e32 v68, 16, v69
	v_and_b32_e32 v69, 0xffff0000, v69
	v_pk_mul_f32 v[74:75], v[78:79], s[10:11] op_sel_hi:[1,0]
	v_pk_mul_f32 v[78:79], v[82:83], s[10:11] op_sel_hi:[1,0]
	v_pk_mul_f32 v[82:83], v[84:85], s[10:11] op_sel_hi:[1,0]
	v_pk_mul_f32 v[84:85], v[88:89], s[10:11] op_sel_hi:[1,0]
	v_pk_fma_f32 v[62:63], v[62:63], v[74:75], v[80:81]
	v_pk_fma_f32 v[64:65], v[64:65], v[78:79], v[66:67]
	v_pk_fma_f32 v[66:67], v[58:59], v[82:83], v[86:87]
	v_pk_fma_f32 v[68:69], v[60:61], v[84:85], v[68:69]
	v_cvt_pk_bf16_f32 v58, v62, v63
	v_cvt_pk_bf16_f32 v59, v64, v65
	v_cvt_pk_bf16_f32 v60, v66, v67
	v_cvt_pk_bf16_f32 v61, v68, v69
	global_store_dwordx4 v[70:71], v[58:61], off sc1
	s_nop 0
	s_nop 0
	s_nop 0
	s_waitcnt vmcnt(2)
	v_cvt_f32_ubyte1_e32 v65, v200
	v_cvt_f32_ubyte0_e32 v64, v200
	v_cvt_f32_ubyte3_e32 v69, v200
	v_cvt_f32_ubyte2_e32 v68, v200
	v_cvt_f32_ubyte1_e32 v73, v201
	v_cvt_f32_ubyte0_e32 v72, v201
	v_cvt_f32_ubyte3_e32 v77, v201
	v_cvt_f32_ubyte2_e32 v76, v201
	s_waitcnt vmcnt(1)
	v_lshlrev_b32_e32 v66, 16, v204
	v_and_b32_e32 v67, 0xffff0000, v204
	v_lshlrev_b32_e32 v58, 16, v205
	v_and_b32_e32 v59, 0xffff0000, v205
	v_lshlrev_b32_e32 v74, 16, v206
	v_and_b32_e32 v75, 0xffff0000, v206
	v_lshlrev_b32_e32 v60, 16, v207
	v_and_b32_e32 v61, 0xffff0000, v207
	v_pk_mul_f32 v[62:63], v[64:65], s[10:11] op_sel_hi:[1,0]
	v_pk_mul_f32 v[64:65], v[68:69], s[10:11] op_sel_hi:[1,0]
	v_pk_mul_f32 v[68:69], v[72:73], s[10:11] op_sel_hi:[1,0]
	v_pk_mul_f32 v[72:73], v[76:77], s[10:11] op_sel_hi:[1,0]
	v_pk_fma_f32 v[54:55], v[54:55], v[62:63], v[66:67]
	v_pk_fma_f32 v[56:57], v[56:57], v[64:65], v[58:59]
	v_pk_fma_f32 v[58:59], v[50:51], v[68:69], v[74:75]
	v_pk_fma_f32 v[60:61], v[52:53], v[72:73], v[60:61]
	v_cvt_pk_bf16_f32 v50, v54, v55
	v_cvt_pk_bf16_f32 v51, v56, v57
	v_cvt_pk_bf16_f32 v52, v58, v59
	v_cvt_pk_bf16_f32 v53, v60, v61
	global_store_dwordx4 v[70:71], v[50:53], off offset:256 sc1
	v_lshl_add_u64 v[54:55], v[138:139], 0, s[12:13]
	s_nop 0
	v_lshl_add_u64 v[50:51], s[22:23], 0, v[54:55]
	v_lshl_add_u64 v[56:57], v[50:51], 0, v[136:137]
	v_lshl_add_u64 v[50:51], s[20:21], 0, v[54:55]
	global_load_dwordx2 v[58:59], v[56:57], off offset:1024
	v_lshl_add_u64 v[60:61], v[50:51], 0, v[134:135]
	global_load_dwordx4 v[50:53], v[60:61], off
	global_load_dwordx2 v[200:201], v[56:57], off offset:1152
	global_load_dwordx4 v[204:207], v[60:61], off offset:256
	v_lshl_add_u64 v[54:55], s[36:37], 0, v[54:55]
	v_lshl_add_u64 v[54:55], v[54:55], 0, v[134:135]
	s_waitcnt vmcnt(3)
	v_cvt_f32_ubyte1_e32 v63, v58
	v_cvt_f32_ubyte0_e32 v62, v58
	v_cvt_f32_ubyte3_e32 v67, v58
	v_cvt_f32_ubyte2_e32 v66, v58
	v_cvt_f32_ubyte1_e32 v69, v59
	v_cvt_f32_ubyte0_e32 v68, v59
	v_cvt_f32_ubyte3_e32 v73, v59
	v_cvt_f32_ubyte2_e32 v72, v59
	s_waitcnt vmcnt(2)
	v_lshlrev_b32_e32 v64, 16, v50
	v_and_b32_e32 v65, 0xffff0000, v50
	v_lshlrev_b32_e32 v50, 16, v51
	v_and_b32_e32 v51, 0xffff0000, v51
	v_lshlrev_b32_e32 v70, 16, v52
	v_and_b32_e32 v71, 0xffff0000, v52
	v_lshlrev_b32_e32 v52, 16, v53
	v_and_b32_e32 v53, 0xffff0000, v53
	v_pk_mul_f32 v[58:59], v[62:63], s[10:11] op_sel_hi:[1,0]
	v_pk_mul_f32 v[62:63], v[66:67], s[10:11] op_sel_hi:[1,0]
	v_pk_mul_f32 v[66:67], v[68:69], s[10:11] op_sel_hi:[1,0]
	v_pk_mul_f32 v[68:69], v[72:73], s[10:11] op_sel_hi:[1,0]
	v_pk_fma_f32 v[46:47], v[46:47], v[58:59], v[64:65]
	v_pk_fma_f32 v[48:49], v[48:49], v[62:63], v[50:51]
	v_pk_fma_f32 v[50:51], v[42:43], v[66:67], v[70:71]
	v_pk_fma_f32 v[52:53], v[44:45], v[68:69], v[52:53]
	v_cvt_pk_bf16_f32 v42, v46, v47
	v_cvt_pk_bf16_f32 v43, v48, v49
	v_cvt_pk_bf16_f32 v44, v50, v51
	v_cvt_pk_bf16_f32 v45, v52, v53
	global_store_dwordx4 v[54:55], v[42:45], off sc1
	s_nop 0
	s_nop 0
	s_nop 0
	s_waitcnt vmcnt(2)
; __device__ __forceinline__ float bflo(unsigned w) { return __uint_as_float(w << 16); }
; __device__ __forceinline__ float bfhi(unsigned w) { return __uint_as_float(w & 0xffff0000u); }
; #define EPI_ROWS(...) _Pragma("unroll") for (int ai = 0; ai < 2; ++ai) _Pragma("unroll") for (int m = 0; m < 4; ++m) { const int row = row0 + ai * 128 + m * 16; __VA_ARGS__ __builtin_amdgcn_sched_barrier(0); }
; __device__ __forceinline__ u32x4 pack8(f32x4 a, f32x4 b) { u32x4 w; w.x = pk2(a[0], a[1]); w.y = pk2(a[2], a[3]); w.z = pk2(b[0], b[1]); w.w = pk2(b[2], b[3]); return w; }
;     __device__ __forceinline__ void operator()(AccRef acc, const Unit& u, int wr, int wc, int fr, int fq) const {
;         const int row0 = u.pm * 256 + wr * 64 + fr, col0 = u.pn * 256 + wc * 32 + 8 * fq;
;         EPI_ROWS(
;             _Pragma("unroll") for (int bj = 0; bj < 2; ++bj) { const int col = col0 + bj * 128;
;                 const u32x2 gw = *(const u32x2*)(ZG8 + (size_t)row * 2048 + WHICH * 1024 + col);
;                 f32x4 v[2];
;                 _Pragma("unroll") for (int n = 0; n < 2; ++n) _Pragma("unroll") for (int i = 0; i < 4; ++i) v[n][i] = acc[ai][bj][m][n][i] * ((float)((gw[n] >> (8 * i)) & 255u) * (1.f / 255.f));
;                 if (WHICH == 0) *(u32x4*)(M1 + (size_t)row * 1024 + col) = pack8(v[0], v[1]);
;                 else { const u32x4 mw = *(const u32x4*)(M1 + (size_t)row * 1024 + col);
;                     _Pragma("unroll") for (int n = 0; n < 2; ++n) { v[n][0] += bflo(mw[2 * n]); v[n][1] += bfhi(mw[2 * n]); v[n][2] += bflo(mw[2 * n + 1]); v[n][3] += bfhi(mw[2 * n + 1]); }
;                     *(u32x4*)(MB + (size_t)row * 1024 + col) = pack8(v[0], v[1]); } }
	v_cvt_f32_ubyte1_e32 v49, v200
	v_cvt_f32_ubyte0_e32 v48, v200
	v_cvt_f32_ubyte3_e32 v53, v200
	v_cvt_f32_ubyte2_e32 v52, v200
	v_cvt_f32_ubyte1_e32 v57, v201
	v_cvt_f32_ubyte0_e32 v56, v201
	v_cvt_f32_ubyte3_e32 v61, v201
	v_cvt_f32_ubyte2_e32 v60, v201
	s_waitcnt vmcnt(1)
	v_lshlrev_b32_e32 v50, 16, v204
	v_and_b32_e32 v51, 0xffff0000, v204
	v_lshlrev_b32_e32 v42, 16, v205
	v_and_b32_e32 v43, 0xffff0000, v205
	v_lshlrev_b32_e32 v58, 16, v206
	v_and_b32_e32 v59, 0xffff0000, v206
	v_lshlrev_b32_e32 v44, 16, v207
	v_and_b32_e32 v45, 0xffff0000, v207
	v_pk_mul_f32 v[46:47], v[48:49], s[10:11] op_sel_hi:[1,0]
	v_pk_mul_f32 v[48:49], v[52:53], s[10:11] op_sel_hi:[1,0]
	v_pk_mul_f32 v[52:53], v[56:57], s[10:11] op_sel_hi:[1,0]
	v_pk_mul_f32 v[56:57], v[60:61], s[10:11] op_sel_hi:[1,0]
	v_pk_fma_f32 v[38:39], v[38:39], v[46:47], v[50:51]
	v_pk_fma_f32 v[40:41], v[40:41], v[48:49], v[42:43]
	v_pk_fma_f32 v[42:43], v[34:35], v[52:53], v[58:59]
	v_pk_fma_f32 v[44:45], v[36:37], v[56:57], v[44:45]
	v_cvt_pk_bf16_f32 v34, v38, v39
	v_cvt_pk_bf16_f32 v35, v40, v41
	v_cvt_pk_bf16_f32 v36, v42, v43
	v_cvt_pk_bf16_f32 v37, v44, v45
	global_store_dwordx4 v[54:55], v[34:37], off offset:256 sc1
	v_lshl_add_u64 v[38:39], v[138:139], 0, s[38:39]
	s_nop 0
	v_lshl_add_u64 v[34:35], s[22:23], 0, v[38:39]
	v_lshl_add_u64 v[40:41], v[34:35], 0, v[136:137]
	v_lshl_add_u64 v[34:35], s[20:21], 0, v[38:39]
	global_load_dwordx2 v[42:43], v[40:41], off offset:1024
	v_lshl_add_u64 v[44:45], v[34:35], 0, v[134:135]
	global_load_dwordx4 v[34:37], v[44:45], off
	global_load_dwordx2 v[200:201], v[40:41], off offset:1152
	global_load_dwordx4 v[204:207], v[44:45], off offset:256
	v_lshl_add_u64 v[38:39], s[36:37], 0, v[38:39]
	v_lshl_add_u64 v[38:39], v[38:39], 0, v[134:135]
	s_waitcnt vmcnt(3)
	v_cvt_f32_ubyte1_e32 v47, v42
	v_cvt_f32_ubyte0_e32 v46, v42
	v_cvt_f32_ubyte3_e32 v51, v42
	v_cvt_f32_ubyte2_e32 v50, v42
	v_cvt_f32_ubyte1_e32 v53, v43
	v_cvt_f32_ubyte0_e32 v52, v43
	v_cvt_f32_ubyte3_e32 v57, v43
	v_cvt_f32_ubyte2_e32 v56, v43
	s_waitcnt vmcnt(2)
	v_lshlrev_b32_e32 v48, 16, v34
	v_and_b32_e32 v49, 0xffff0000, v34
	v_lshlrev_b32_e32 v34, 16, v35
	v_and_b32_e32 v35, 0xffff0000, v35
	v_lshlrev_b32_e32 v54, 16, v36
	v_and_b32_e32 v55, 0xffff0000, v36
	v_lshlrev_b32_e32 v36, 16, v37
	v_and_b32_e32 v37, 0xffff0000, v37
	v_pk_mul_f32 v[42:43], v[46:47], s[10:11] op_sel_hi:[1,0]
	v_pk_mul_f32 v[46:47], v[50:51], s[10:11] op_sel_hi:[1,0]
	v_pk_mul_f32 v[50:51], v[52:53], s[10:11] op_sel_hi:[1,0]
	v_pk_mul_f32 v[52:53], v[56:57], s[10:11] op_sel_hi:[1,0]
	v_pk_fma_f32 v[30:31], v[30:31], v[42:43], v[48:49]
	v_pk_fma_f32 v[32:33], v[32:33], v[46:47], v[34:35]
	v_pk_fma_f32 v[34:35], v[26:27], v[50:51], v[54:55]
	v_pk_fma_f32 v[36:37], v[28:29], v[52:53], v[36:37]
	v_cvt_pk_bf16_f32 v26, v30, v31
	v_cvt_pk_bf16_f32 v27, v32, v33
	v_cvt_pk_bf16_f32 v28, v34, v35
	v_cvt_pk_bf16_f32 v29, v36, v37
	global_store_dwordx4 v[38:39], v[26:29], off sc1
	s_nop 0
	s_nop 0
	s_nop 0
	s_waitcnt vmcnt(2)
	v_cvt_f32_ubyte1_e32 v33, v200
	v_cvt_f32_ubyte0_e32 v32, v200
	v_cvt_f32_ubyte3_e32 v37, v200
	v_cvt_f32_ubyte2_e32 v36, v200
	v_cvt_f32_ubyte1_e32 v41, v201
	v_cvt_f32_ubyte0_e32 v40, v201
	v_cvt_f32_ubyte3_e32 v45, v201
	v_cvt_f32_ubyte2_e32 v44, v201
	s_waitcnt vmcnt(1)
; __device__ __forceinline__ float bflo(unsigned w) { return __uint_as_float(w << 16); }
; __device__ __forceinline__ float bfhi(unsigned w) { return __uint_as_float(w & 0xffff0000u); }
; #define PG8_BAR __builtin_amdgcn_s_barrier()
; #define EPI_ROWS(...) _Pragma("unroll") for (int ai = 0; ai < 2; ++ai) _Pragma("unroll") for (int m = 0; m < 4; ++m) { const int row = row0 + ai * 128 + m * 16; __VA_ARGS__ __builtin_amdgcn_sched_barrier(0); }
; __device__ __forceinline__ u32x4 pack8(f32x4 a, f32x4 b) { u32x4 w; w.x = pk2(a[0], a[1]); w.y = pk2(a[2], a[3]); w.z = pk2(b[0], b[1]); w.w = pk2(b[2], b[3]); return w; }
; template <class Epi>
; __device__ __forceinline__ void gemm_phase(LAS unsigned char* lds, const Gemm g, const StaticOrder& S, const Epi& E) {
;     ...
;         if (!has_next) break;
; #pragma unroll
;         for (int a = 0; a < 2; ++a)
; #pragma unroll
;             for (int b = 0; b < 2; ++b)
; #pragma unroll
;                 for (int m = 0; m < 4; ++m)
; #pragma unroll
;                     for (int n = 0; n < 2; ++n) acc[a][b][m][n] = (f32x4){0.f, 0.f, 0.f, 0.f};
;         cur = nxt; cA = nA; cB = nB; ++ui;
;         if (wr == 1) PG8_BAR;
;     __device__ __forceinline__ void operator()(AccRef acc, const Unit& u, int wr, int wc, int fr, int fq) const {
;         const int row0 = u.pm * 256 + wr * 64 + fr, col0 = u.pn * 256 + wc * 32 + 8 * fq;
;         EPI_ROWS(
;             _Pragma("unroll") for (int bj = 0; bj < 2; ++bj) { const int col = col0 + bj * 128;
;                 const u32x2 gw = *(const u32x2*)(ZG8 + (size_t)row * 2048 + WHICH * 1024 + col);
;                 f32x4 v[2];
;                 _Pragma("unroll") for (int n = 0; n < 2; ++n) _Pragma("unroll") for (int i = 0; i < 4; ++i) v[n][i] = acc[ai][bj][m][n][i] * ((float)((gw[n] >> (8 * i)) & 255u) * (1.f / 255.f));
;                 if (WHICH == 0) *(u32x4*)(M1 + (size_t)row * 1024 + col) = pack8(v[0], v[1]);
;                 else { const u32x4 mw = *(const u32x4*)(M1 + (size_t)row * 1024 + col);
;                     _Pragma("unroll") for (int n = 0; n < 2; ++n) { v[n][0] += bflo(mw[2 * n]); v[n][1] += bfhi(mw[2 * n]); v[n][2] += bflo(mw[2 * n + 1]); v[n][3] += bfhi(mw[2 * n + 1]); }
;                     *(u32x4*)(MB + (size_t)row * 1024 + col) = pack8(v[0], v[1]); } }
	v_lshlrev_b32_e32 v34, 16, v204
	v_and_b32_e32 v35, 0xffff0000, v204
	v_lshlrev_b32_e32 v26, 16, v205
	v_and_b32_e32 v27, 0xffff0000, v205
	v_lshlrev_b32_e32 v42, 16, v206
	v_and_b32_e32 v43, 0xffff0000, v206
	v_lshlrev_b32_e32 v28, 16, v207
	v_and_b32_e32 v29, 0xffff0000, v207
	v_pk_mul_f32 v[30:31], v[32:33], s[10:11] op_sel_hi:[1,0]
	v_pk_mul_f32 v[32:33], v[36:37], s[10:11] op_sel_hi:[1,0]
	v_pk_mul_f32 v[36:37], v[40:41], s[10:11] op_sel_hi:[1,0]
	v_pk_mul_f32 v[40:41], v[44:45], s[10:11] op_sel_hi:[1,0]
	v_pk_fma_f32 v[22:23], v[22:23], v[30:31], v[34:35]
	v_pk_fma_f32 v[24:25], v[24:25], v[32:33], v[26:27]
	v_pk_fma_f32 v[26:27], v[18:19], v[36:37], v[42:43]
	v_pk_fma_f32 v[28:29], v[20:21], v[40:41], v[28:29]
	v_cvt_pk_bf16_f32 v18, v22, v23
	v_cvt_pk_bf16_f32 v19, v24, v25
	v_cvt_pk_bf16_f32 v20, v26, v27
	v_cvt_pk_bf16_f32 v21, v28, v29
	global_store_dwordx4 v[38:39], v[18:21], off offset:256 sc1
	v_lshl_add_u64 v[22:23], v[138:139], 0, s[42:43]
	s_nop 0
	v_lshl_add_u64 v[18:19], s[22:23], 0, v[22:23]
	v_lshl_add_u64 v[24:25], v[18:19], 0, v[136:137]
	v_lshl_add_u64 v[18:19], s[20:21], 0, v[22:23]
	global_load_dwordx2 v[26:27], v[24:25], off offset:1024
	v_lshl_add_u64 v[28:29], v[18:19], 0, v[134:135]
	global_load_dwordx4 v[18:21], v[28:29], off
	global_load_dwordx2 v[200:201], v[24:25], off offset:1152
	global_load_dwordx4 v[204:207], v[28:29], off offset:256
	v_lshl_add_u64 v[22:23], s[36:37], 0, v[22:23]
	v_lshl_add_u64 v[22:23], v[22:23], 0, v[134:135]
	s_waitcnt vmcnt(3)
	v_cvt_f32_ubyte1_e32 v31, v26
	v_cvt_f32_ubyte0_e32 v30, v26
	v_cvt_f32_ubyte3_e32 v35, v26
	v_cvt_f32_ubyte2_e32 v34, v26
	v_cvt_f32_ubyte1_e32 v37, v27
	v_cvt_f32_ubyte0_e32 v36, v27
	v_cvt_f32_ubyte3_e32 v41, v27
	v_cvt_f32_ubyte2_e32 v40, v27
	s_waitcnt vmcnt(2)
	v_lshlrev_b32_e32 v32, 16, v18
	v_and_b32_e32 v33, 0xffff0000, v18
	v_lshlrev_b32_e32 v18, 16, v19
	v_and_b32_e32 v19, 0xffff0000, v19
	v_lshlrev_b32_e32 v38, 16, v20
	v_and_b32_e32 v39, 0xffff0000, v20
	v_lshlrev_b32_e32 v20, 16, v21
	v_and_b32_e32 v21, 0xffff0000, v21
	v_pk_mul_f32 v[26:27], v[30:31], s[10:11] op_sel_hi:[1,0]
	v_pk_mul_f32 v[30:31], v[34:35], s[10:11] op_sel_hi:[1,0]
	v_pk_mul_f32 v[34:35], v[36:37], s[10:11] op_sel_hi:[1,0]
	v_pk_mul_f32 v[36:37], v[40:41], s[10:11] op_sel_hi:[1,0]
	v_pk_fma_f32 v[14:15], v[14:15], v[26:27], v[32:33]
	v_pk_fma_f32 v[16:17], v[16:17], v[30:31], v[18:19]
	v_pk_fma_f32 v[18:19], v[10:11], v[34:35], v[38:39]
	v_pk_fma_f32 v[20:21], v[12:13], v[36:37], v[20:21]
	v_cvt_pk_bf16_f32 v10, v14, v15
	v_cvt_pk_bf16_f32 v11, v16, v17
	v_cvt_pk_bf16_f32 v12, v18, v19
	v_cvt_pk_bf16_f32 v13, v20, v21
	global_store_dwordx4 v[22:23], v[10:13], off sc1
	s_nop 0
	s_nop 0
	s_nop 0
	s_waitcnt vmcnt(2)
	v_cvt_f32_ubyte1_e32 v17, v200
	v_cvt_f32_ubyte0_e32 v16, v200
	v_cvt_f32_ubyte3_e32 v21, v200
	v_cvt_f32_ubyte2_e32 v20, v200
	v_cvt_f32_ubyte1_e32 v25, v201
	v_cvt_f32_ubyte0_e32 v24, v201
	v_cvt_f32_ubyte3_e32 v29, v201
	v_cvt_f32_ubyte2_e32 v28, v201
	s_waitcnt vmcnt(1)
	v_lshlrev_b32_e32 v18, 16, v204
	v_and_b32_e32 v19, 0xffff0000, v204
	v_lshlrev_b32_e32 v10, 16, v205
	v_and_b32_e32 v11, 0xffff0000, v205
	v_lshlrev_b32_e32 v26, 16, v206
	v_and_b32_e32 v27, 0xffff0000, v206
	v_lshlrev_b32_e32 v12, 16, v207
	v_and_b32_e32 v13, 0xffff0000, v207
	v_pk_mul_f32 v[14:15], v[16:17], s[10:11] op_sel_hi:[1,0]
	v_pk_mul_f32 v[16:17], v[20:21], s[10:11] op_sel_hi:[1,0]
	v_pk_mul_f32 v[20:21], v[24:25], s[10:11] op_sel_hi:[1,0]
	v_pk_mul_f32 v[24:25], v[28:29], s[10:11] op_sel_hi:[1,0]
	v_pk_fma_f32 v[6:7], v[6:7], v[14:15], v[18:19]
	v_pk_fma_f32 v[8:9], v[8:9], v[16:17], v[10:11]
	v_pk_fma_f32 v[10:11], v[2:3], v[20:21], v[26:27]
	v_pk_fma_f32 v[12:13], v[4:5], v[24:25], v[12:13]
	v_cvt_pk_bf16_f32 v2, v6, v7
	v_cvt_pk_bf16_f32 v3, v8, v9
	v_cvt_pk_bf16_f32 v4, v10, v11
	v_cvt_pk_bf16_f32 v5, v12, v13
	global_store_dwordx4 v[22:23], v[2:5], off offset:256 sc1
	s_andn2_b64 vcc, exec, s[4:5]
	s_mov_b64 s[4:5], -1
	s_cbranch_vccnz .LBB0_1287
	s_andn2_b64 vcc, exec, s[6:7]
	s_cbranch_vccnz .LBB0_1286
	s_barrier
	s_branch .LBB0_1286

; #define EPI_ROWS(...) _Pragma("unroll") for (int ai = 0; ai < 2; ++ai) _Pragma("unroll") for (int m = 0; m < 4; ++m) { const int row = row0 + ai * 128 + m * 16; __VA_ARGS__ __builtin_amdgcn_sched_barrier(0); }
; __device__ __forceinline__ u32x4 pack8(f32x4 a, f32x4 b) { u32x4 w; w.x = pk2(a[0], a[1]); w.y = pk2(a[2], a[3]); w.z = pk2(b[0], b[1]); w.w = pk2(b[2], b[3]); return w; }
; __device__ __forceinline__ float dot8(f32x4 a, f32x4 b) { return (a[0] * a[0] + a[1] * a[1]) + (a[2] * a[2] + a[3] * a[3]) + (b[0] * b[0] + b[1] * b[1]) + (b[2] * b[2] + b[3] * b[3]); }
; __device__ __forceinline__ float red_fq(float s) { s += __shfl_xor(s, 16); s += __shfl_xor(s, 32); return s; }
;     __device__ __forceinline__ void operator()(AccRef acc, const Unit& u, int wr, int wc, int fr, int fq) const {
;         const int row0 = u.pm * 256 + wr * 64 + fr, col0 = u.pn * 256 + wc * 32 + 8 * fq;
;         EPI_ROWS(
;             const float* rp = (row < MP) ? res0 + (size_t)row * DM : res1 + (size_t)(row - MP) * DM;
;             float s = 0.f;
;             _Pragma("unroll") for (int bj = 0; bj < 2; ++bj) { const int col = col0 + bj * 128;
;                 f32x4 v0 = *(const f32x4*)(rp + col) + acc[ai][bj][m][0] * scale, v1 = *(const f32x4*)(rp + col + 4) + acc[ai][bj][m][1] * scale;
;                 *(f32x4*)(out + (size_t)row * DM + col) = v0; *(f32x4*)(out + (size_t)row * DM + col + 4) = v1;
;                 if (WB) *(u32x4*)(ob + (size_t)row * DM + col) = pack8(v0, v1);
;                 s += dot8(v0, v1); }
;             s = red_fq(s); if (fq == 0) unsafeAtomicAdd(ss + row, s);
;         )
.LBB0_1395:
	v_lshl_add_u32 v146, s54, 8, v155
	v_cmp_lt_i32_e32 vcc, s79, v146
	s_and_saveexec_b64 s[16:17], vcc
	s_xor_b64 s[16:17], exec, s[16:17]
	v_add_u32_e32 v136, 0xffff8000, v146
	v_mov_b32_e32 v137, v2
	v_lshlrev_b64 v[136:137], 12, v[136:137]
	v_lshl_add_u64 v[148:149], s[10:11], 0, v[136:137]
	v_mov_b32_e32 v147, v2
	s_andn2_saveexec_b64 s[16:17], s[16:17]
	v_ashrrev_i32_e32 v147, 31, v146
	v_lshlrev_b64 v[136:137], 12, v[146:147]
	v_lshl_add_u64 v[148:149], s[30:31], 0, v[136:137]
	s_or_b64 exec, exec, s[16:17]
	v_lshl_or_b32 v142, s52, 8, v188
	v_ashrrev_i32_e32 v143, 31, v142
	v_lshlrev_b64 v[144:145], 2, v[142:143]
	v_lshl_add_u64 v[148:149], v[148:149], 0, v[144:145]
	global_load_dwordx4 v[136:139], v[148:149], off
	global_load_dwordx4 v[196:199], v[148:149], off offset:16
	global_load_dwordx4 v[216:219], v[148:149], off offset:512
	global_load_dwordx4 v[220:223], v[148:149], off offset:528
	v_lshlrev_b64 v[200:201], 12, v[146:147]
	v_lshlrev_b64 v[202:203], 11, v[146:147]
	v_lshl_add_u64 v[200:201], s[30:31], 0, v[200:201]
	v_lshl_add_u64 v[202:203], s[18:19], 0, v[202:203]
	v_lshl_add_u64 v[202:203], v[142:143], 1, v[202:203]
	v_lshl_add_u64 v[200:201], v[200:201], 0, v[144:145]
	v_xor_b32_e32 v3, 16, v193
	s_waitcnt vmcnt(3)
	v_pk_add_f32 v[130:131], v[138:139], v[130:131]
	v_pk_add_f32 v[128:129], v[136:137], v[128:129]
	s_waitcnt vmcnt(2)
	v_pk_add_f32 v[126:127], v[198:199], v[126:127]
	v_pk_add_f32 v[124:125], v[196:197], v[124:125]
	v_cvt_pk_bf16_f32 v136, v128, v129
	v_cvt_pk_bf16_f32 v137, v130, v131
	v_cvt_pk_bf16_f32 v138, v124, v125
	v_cvt_pk_bf16_f32 v139, v126, v127
	global_store_dwordx4 v[200:201], v[128:131], off
	global_store_dwordx4 v[200:201], v[124:127], off offset:16
	global_store_dwordx4 v[202:203], v[136:139], off sc1
	s_nop 0
	s_nop 0
	s_nop 0
	v_mul_f32_e32 v129, v129, v129
	v_mul_f32_e32 v131, v131, v131
	v_mul_f32_e32 v125, v125, v125
	v_fmac_f32_e32 v129, v128, v128
	v_fmac_f32_e32 v131, v130, v130
	v_mul_f32_e32 v127, v127, v127
	v_fmac_f32_e32 v125, v124, v124
	v_add_f32_e32 v124, v129, v131
	v_fmac_f32_e32 v127, v126, v126
	v_add_f32_e32 v124, v125, v124
	v_add_f32_e32 v130, v127, v124
	v_and_b32_e32 v148, 64, v193
	v_add_u32_e32 v148, 64, v148
	v_cmp_lt_i32_e32 vcc, v3, v148
	v_xor_b32_e32 v149, 32, v193
	s_waitcnt vmcnt(4)
	v_pk_add_f32 v[124:125], v[218:219], v[122:123]
	v_pk_add_f32 v[122:123], v[216:217], v[120:121]
	s_waitcnt vmcnt(3)
	v_pk_add_f32 v[126:127], v[220:221], v[116:117]
	v_mul_f32_e32 v116, v123, v123
	v_mul_f32_e32 v117, v125, v125
	v_pk_add_f32 v[128:129], v[222:223], v[118:119]
	v_mul_f32_e32 v118, v127, v127
	v_fmac_f32_e32 v116, v122, v122
	v_fmac_f32_e32 v117, v124, v124
	v_mul_f32_e32 v119, v129, v129
	v_fmac_f32_e32 v118, v126, v126
	v_add_f32_e32 v116, v116, v117
	v_add_f32_e32 v116, v118, v116
	v_fmac_f32_e32 v119, v128, v128
	v_cndmask_b32_e32 v3, v193, v3, vcc
	v_add_f32_e32 v116, v119, v116
	v_lshlrev_b32_e32 v3, 2, v3
	v_add_f32_e32 v116, v130, v116
	ds_bpermute_b32 v117, v3, v116
	v_cmp_lt_i32_e32 vcc, v149, v148
	global_store_dwordx4 v[200:201], v[122:125], off offset:512
	global_store_dwordx4 v[200:201], v[126:129], off offset:528
	v_cndmask_b32_e32 v148, v193, v149, vcc
	v_lshlrev_b32_e32 v120, 2, v148
	s_waitcnt lgkmcnt(0)
	v_add_f32_e32 v116, v116, v117
	ds_bpermute_b32 v117, v120, v116
	v_cvt_pk_bf16_f32 v122, v122, v123
	v_cvt_pk_bf16_f32 v123, v124, v125
	v_cvt_pk_bf16_f32 v124, v126, v127
	v_cvt_pk_bf16_f32 v125, v128, v129
	global_store_dwordx4 v[202:203], v[122:125], off offset:256 sc1
	s_and_saveexec_b64 s[16:17], s[6:7]
	s_cbranch_execz .LBB0_1401
	s_waitcnt lgkmcnt(0)
	v_add_f32_e32 v118, v116, v117
	v_lshl_add_u64 v[116:117], v[146:147], 2, s[12:13]
	v_mov_b32_e32 v224, v116
	v_mov_b32_e32 v225, v117
	v_mov_b32_e32 v226, v118
.LBB0_1401:
	s_or_b64 exec, exec, s[16:17]
	s_waitcnt lgkmcnt(0)
	v_or_b32_e32 v116, 16, v146
	v_cmp_lt_i32_e32 vcc, s79, v116
	s_and_saveexec_b64 s[16:17], vcc
	s_xor_b64 s[16:17], exec, s[16:17]
	v_add_u32_e32 v118, 0xffff8010, v146
	v_mov_b32_e32 v119, v2
	v_lshlrev_b64 v[118:119], 12, v[118:119]
	v_lshl_add_u64 v[118:119], s[10:11], 0, v[118:119]
	v_mov_b32_e32 v117, v2
	s_andn2_saveexec_b64 s[16:17], s[16:17]
	v_ashrrev_i32_e32 v117, 31, v116
	v_lshlrev_b64 v[118:119], 12, v[116:117]
	v_lshl_add_u64 v[118:119], s[30:31], 0, v[118:119]
	s_or_b64 exec, exec, s[16:17]
	v_lshl_add_u64 v[118:119], v[118:119], 0, v[144:145]
	global_load_dwordx4 v[122:125], v[118:119], off
	global_load_dwordx4 v[126:129], v[118:119], off offset:16
	global_load_dwordx4 v[216:219], v[118:119], off offset:512
	global_load_dwordx4 v[220:223], v[118:119], off offset:528
	v_lshlrev_b64 v[130:131], 12, v[116:117]
	v_lshlrev_b64 v[136:137], 11, v[116:117]
	v_lshl_add_u64 v[130:131], s[30:31], 0, v[130:131]
	v_lshl_add_u64 v[136:137], s[18:19], 0, v[136:137]
	v_lshl_add_u64 v[130:131], v[130:131], 0, v[144:145]
	v_lshl_add_u64 v[136:137], v[142:143], 1, v[136:137]
	s_waitcnt vmcnt(3)
	v_pk_add_f32 v[114:115], v[124:125], v[114:115]
	v_pk_add_f32 v[112:113], v[122:123], v[112:113]
	s_waitcnt vmcnt(2)
	v_pk_add_f32 v[110:111], v[128:129], v[110:111]
	v_pk_add_f32 v[108:109], v[126:127], v[108:109]
	v_cvt_pk_bf16_f32 v122, v112, v113
	v_cvt_pk_bf16_f32 v123, v114, v115
	v_cvt_pk_bf16_f32 v124, v108, v109
	v_cvt_pk_bf16_f32 v125, v110, v111
	global_store_dwordx4 v[130:131], v[112:115], off
	global_store_dwordx4 v[130:131], v[108:111], off offset:16
	global_store_dwordx4 v[136:137], v[122:125], off sc1
	s_nop 0
	s_nop 0
	s_nop 0
	v_mul_f32_e32 v113, v113, v113
	v_mul_f32_e32 v115, v115, v115
	v_mul_f32_e32 v109, v109, v109
	v_fmac_f32_e32 v113, v112, v112
	v_fmac_f32_e32 v115, v114, v114
	v_mul_f32_e32 v111, v111, v111
	v_fmac_f32_e32 v109, v108, v108
	v_add_f32_e32 v108, v113, v115
	v_fmac_f32_e32 v111, v110, v110
	v_add_f32_e32 v108, v109, v108
	v_add_f32_e32 v112, v111, v108
	s_waitcnt vmcnt(4)
	v_pk_add_f32 v[106:107], v[218:219], v[106:107]
	v_pk_add_f32 v[104:105], v[216:217], v[104:105]
	s_waitcnt vmcnt(3)
	v_pk_add_f32 v[108:109], v[220:221], v[100:101]
	v_mul_f32_e32 v100, v105, v105
	v_mul_f32_e32 v101, v107, v107
	v_pk_add_f32 v[110:111], v[222:223], v[102:103]
	v_mul_f32_e32 v102, v109, v109
	v_fmac_f32_e32 v100, v104, v104
	v_fmac_f32_e32 v101, v106, v106
	v_mul_f32_e32 v103, v111, v111
	v_fmac_f32_e32 v102, v108, v108
	v_add_f32_e32 v100, v100, v101
	v_add_f32_e32 v100, v102, v100
	v_fmac_f32_e32 v103, v110, v110
	v_add_f32_e32 v100, v103, v100
	v_add_f32_e32 v100, v112, v100
	ds_bpermute_b32 v101, v3, v100
	global_store_dwordx4 v[130:131], v[104:107], off offset:512
	global_store_dwordx4 v[130:131], v[108:111], off offset:528
	v_cvt_pk_bf16_f32 v102, v104, v105
	v_cvt_pk_bf16_f32 v103, v106, v107
	v_cvt_pk_bf16_f32 v104, v108, v109
	s_waitcnt lgkmcnt(0)
	v_add_f32_e32 v100, v100, v101
	ds_bpermute_b32 v101, v120, v100
	v_cvt_pk_bf16_f32 v105, v110, v111
	global_store_dwordx4 v[136:137], v[102:105], off offset:256 sc1
	s_and_saveexec_b64 s[16:17], s[6:7]
	s_cbranch_execz .LBB0_1407
; #define EPI_ROWS(...) _Pragma("unroll") for (int ai = 0; ai < 2; ++ai) _Pragma("unroll") for (int m = 0; m < 4; ++m) { const int row = row0 + ai * 128 + m * 16; __VA_ARGS__ __builtin_amdgcn_sched_barrier(0); }
; __device__ __forceinline__ u32x4 pack8(f32x4 a, f32x4 b) { u32x4 w; w.x = pk2(a[0], a[1]); w.y = pk2(a[2], a[3]); w.z = pk2(b[0], b[1]); w.w = pk2(b[2], b[3]); return w; }
; __device__ __forceinline__ float dot8(f32x4 a, f32x4 b) { return (a[0] * a[0] + a[1] * a[1]) + (a[2] * a[2] + a[3] * a[3]) + (b[0] * b[0] + b[1] * b[1]) + (b[2] * b[2] + b[3] * b[3]); }
; __device__ __forceinline__ float red_fq(float s) { s += __shfl_xor(s, 16); s += __shfl_xor(s, 32); return s; }
;     __device__ __forceinline__ void operator()(AccRef acc, const Unit& u, int wr, int wc, int fr, int fq) const {
;         const int row0 = u.pm * 256 + wr * 64 + fr, col0 = u.pn * 256 + wc * 32 + 8 * fq;
;         EPI_ROWS(
;             const float* rp = (row < MP) ? res0 + (size_t)row * DM : res1 + (size_t)(row - MP) * DM;
;             float s = 0.f;
;             _Pragma("unroll") for (int bj = 0; bj < 2; ++bj) { const int col = col0 + bj * 128;
;                 f32x4 v0 = *(const f32x4*)(rp + col) + acc[ai][bj][m][0] * scale, v1 = *(const f32x4*)(rp + col + 4) + acc[ai][bj][m][1] * scale;
;                 *(f32x4*)(out + (size_t)row * DM + col) = v0; *(f32x4*)(out + (size_t)row * DM + col + 4) = v1;
;                 if (WB) *(u32x4*)(ob + (size_t)row * DM + col) = pack8(v0, v1);
;                 s += dot8(v0, v1); }
;             s = red_fq(s); if (fq == 0) unsafeAtomicAdd(ss + row, s);
;         )
	s_waitcnt lgkmcnt(0)
	v_add_f32_e32 v102, v100, v101
	v_lshl_add_u64 v[100:101], v[116:117], 2, s[12:13]
	v_mov_b32_e32 v228, v100
	v_mov_b32_e32 v229, v101
	v_mov_b32_e32 v230, v102
.LBB0_1407:
	s_or_b64 exec, exec, s[16:17]
	s_waitcnt lgkmcnt(0)
	v_or_b32_e32 v100, 32, v146
	v_cmp_lt_i32_e32 vcc, s79, v100
	s_and_saveexec_b64 s[16:17], vcc
	s_xor_b64 s[16:17], exec, s[16:17]
	v_add_u32_e32 v102, 0xffff8020, v146
	v_mov_b32_e32 v103, v2
	v_lshlrev_b64 v[102:103], 12, v[102:103]
	v_lshl_add_u64 v[102:103], s[10:11], 0, v[102:103]
	v_mov_b32_e32 v101, v2
	s_andn2_saveexec_b64 s[16:17], s[16:17]
	v_ashrrev_i32_e32 v101, 31, v100
	v_lshlrev_b64 v[102:103], 12, v[100:101]
	v_lshl_add_u64 v[102:103], s[30:31], 0, v[102:103]
	s_or_b64 exec, exec, s[16:17]
	v_lshl_add_u64 v[110:111], v[102:103], 0, v[144:145]
	global_load_dwordx4 v[102:105], v[110:111], off
	global_load_dwordx4 v[106:109], v[110:111], off offset:16
	global_load_dwordx4 v[216:219], v[110:111], off offset:512
	global_load_dwordx4 v[220:223], v[110:111], off offset:528
	v_lshlrev_b64 v[112:113], 12, v[100:101]
	v_lshlrev_b64 v[114:115], 11, v[100:101]
	v_lshl_add_u64 v[112:113], s[30:31], 0, v[112:113]
	v_lshl_add_u64 v[114:115], s[18:19], 0, v[114:115]
	v_lshl_add_u64 v[112:113], v[112:113], 0, v[144:145]
	v_lshl_add_u64 v[114:115], v[142:143], 1, v[114:115]
	s_waitcnt vmcnt(3)
	v_pk_add_f32 v[98:99], v[104:105], v[98:99]
	v_pk_add_f32 v[96:97], v[102:103], v[96:97]
	s_waitcnt vmcnt(2)
	v_pk_add_f32 v[94:95], v[108:109], v[94:95]
	v_pk_add_f32 v[92:93], v[106:107], v[92:93]
	v_cvt_pk_bf16_f32 v102, v96, v97
	v_cvt_pk_bf16_f32 v103, v98, v99
	v_cvt_pk_bf16_f32 v104, v92, v93
	v_cvt_pk_bf16_f32 v105, v94, v95
	global_store_dwordx4 v[112:113], v[96:99], off
	global_store_dwordx4 v[112:113], v[92:95], off offset:16
	global_store_dwordx4 v[114:115], v[102:105], off sc1
	s_nop 0
	s_nop 0
	s_nop 0
	v_mul_f32_e32 v97, v97, v97
	v_mul_f32_e32 v99, v99, v99
	v_mul_f32_e32 v93, v93, v93
	v_fmac_f32_e32 v97, v96, v96
	v_fmac_f32_e32 v99, v98, v98
	v_mul_f32_e32 v95, v95, v95
	v_fmac_f32_e32 v93, v92, v92
	v_add_f32_e32 v92, v97, v99
	v_fmac_f32_e32 v95, v94, v94
	v_add_f32_e32 v92, v93, v92
	v_add_f32_e32 v96, v95, v92
	s_waitcnt vmcnt(4)
	v_pk_add_f32 v[90:91], v[218:219], v[90:91]
	v_pk_add_f32 v[88:89], v[216:217], v[88:89]
	s_waitcnt vmcnt(3)
	v_pk_add_f32 v[92:93], v[220:221], v[84:85]
	v_mul_f32_e32 v84, v89, v89
	v_mul_f32_e32 v85, v91, v91
	v_pk_add_f32 v[94:95], v[222:223], v[86:87]
	v_mul_f32_e32 v86, v93, v93
	v_fmac_f32_e32 v84, v88, v88
	v_fmac_f32_e32 v85, v90, v90
	v_mul_f32_e32 v87, v95, v95
	v_fmac_f32_e32 v86, v92, v92
	v_add_f32_e32 v84, v84, v85
	v_add_f32_e32 v84, v86, v84
	v_fmac_f32_e32 v87, v94, v94
	v_add_f32_e32 v84, v87, v84
	v_add_f32_e32 v84, v96, v84
	ds_bpermute_b32 v85, v3, v84
	global_store_dwordx4 v[112:113], v[88:91], off offset:512
	global_store_dwordx4 v[112:113], v[92:95], off offset:528
	v_cvt_pk_bf16_f32 v86, v88, v89
	v_cvt_pk_bf16_f32 v87, v90, v91
	v_cvt_pk_bf16_f32 v88, v92, v93
	s_waitcnt lgkmcnt(0)
	v_add_f32_e32 v84, v84, v85
	ds_bpermute_b32 v85, v120, v84
	v_cvt_pk_bf16_f32 v89, v94, v95
	global_store_dwordx4 v[114:115], v[86:89], off offset:256 sc1
	s_and_saveexec_b64 s[16:17], s[6:7]
	s_cbranch_execz .LBB0_1413
	s_waitcnt lgkmcnt(0)
	v_add_f32_e32 v86, v84, v85
	v_lshl_add_u64 v[84:85], v[100:101], 2, s[12:13]
	v_mov_b32_e32 v232, v84
	v_mov_b32_e32 v233, v85
	v_mov_b32_e32 v234, v86
.LBB0_1413:
	s_or_b64 exec, exec, s[16:17]
	s_waitcnt lgkmcnt(0)
	v_or_b32_e32 v84, 48, v146
	v_cmp_lt_i32_e32 vcc, s79, v84
	s_and_saveexec_b64 s[16:17], vcc
	s_xor_b64 s[16:17], exec, s[16:17]
	v_add_u32_e32 v86, 0xffff8030, v146
	v_mov_b32_e32 v87, v2
	v_lshlrev_b64 v[86:87], 12, v[86:87]
	v_lshl_add_u64 v[86:87], s[10:11], 0, v[86:87]
	v_mov_b32_e32 v85, v2
	s_andn2_saveexec_b64 s[16:17], s[16:17]
	v_ashrrev_i32_e32 v85, 31, v84
	v_lshlrev_b64 v[86:87], 12, v[84:85]
	v_lshl_add_u64 v[86:87], s[30:31], 0, v[86:87]
	s_or_b64 exec, exec, s[16:17]
	v_lshl_add_u64 v[94:95], v[86:87], 0, v[144:145]
	global_load_dwordx4 v[86:89], v[94:95], off
	global_load_dwordx4 v[90:93], v[94:95], off offset:16
	global_load_dwordx4 v[216:219], v[94:95], off offset:512
	global_load_dwordx4 v[220:223], v[94:95], off offset:528
	v_lshlrev_b64 v[96:97], 12, v[84:85]
	v_lshlrev_b64 v[98:99], 11, v[84:85]
	v_lshl_add_u64 v[96:97], s[30:31], 0, v[96:97]
	v_lshl_add_u64 v[98:99], s[18:19], 0, v[98:99]
	v_lshl_add_u64 v[96:97], v[96:97], 0, v[144:145]
	v_lshl_add_u64 v[98:99], v[142:143], 1, v[98:99]
	s_waitcnt vmcnt(3)
	v_pk_add_f32 v[82:83], v[88:89], v[82:83]
	v_pk_add_f32 v[80:81], v[86:87], v[80:81]
	s_waitcnt vmcnt(2)
	v_pk_add_f32 v[78:79], v[92:93], v[78:79]
	v_pk_add_f32 v[76:77], v[90:91], v[76:77]
	v_cvt_pk_bf16_f32 v86, v80, v81
	v_cvt_pk_bf16_f32 v87, v82, v83
	v_cvt_pk_bf16_f32 v88, v76, v77
	v_cvt_pk_bf16_f32 v89, v78, v79
	global_store_dwordx4 v[96:97], v[80:83], off
	global_store_dwordx4 v[96:97], v[76:79], off offset:16
	global_store_dwordx4 v[98:99], v[86:89], off sc1
	s_nop 0
	s_nop 0
	s_nop 0
	v_mul_f32_e32 v81, v81, v81
	v_mul_f32_e32 v83, v83, v83
	v_mul_f32_e32 v77, v77, v77
	v_fmac_f32_e32 v81, v80, v80
	v_fmac_f32_e32 v83, v82, v82
	v_mul_f32_e32 v79, v79, v79
	v_fmac_f32_e32 v77, v76, v76
	v_add_f32_e32 v76, v81, v83
	v_fmac_f32_e32 v79, v78, v78
	v_add_f32_e32 v76, v77, v76
	v_add_f32_e32 v80, v79, v76
	s_waitcnt vmcnt(4)
	v_pk_add_f32 v[74:75], v[218:219], v[74:75]
	v_pk_add_f32 v[72:73], v[216:217], v[72:73]
	s_waitcnt vmcnt(3)
	v_pk_add_f32 v[76:77], v[220:221], v[68:69]
	v_mul_f32_e32 v68, v73, v73
	v_mul_f32_e32 v69, v75, v75
	v_pk_add_f32 v[78:79], v[222:223], v[70:71]
	v_mul_f32_e32 v70, v77, v77
	v_fmac_f32_e32 v68, v72, v72
	v_fmac_f32_e32 v69, v74, v74
	v_mul_f32_e32 v71, v79, v79
	v_fmac_f32_e32 v70, v76, v76
	v_add_f32_e32 v68, v68, v69
	v_add_f32_e32 v68, v70, v68
	v_fmac_f32_e32 v71, v78, v78
	v_add_f32_e32 v68, v71, v68
	v_add_f32_e32 v68, v80, v68
	ds_bpermute_b32 v69, v3, v68
	global_store_dwordx4 v[96:97], v[72:75], off offset:512
	global_store_dwordx4 v[96:97], v[76:79], off offset:528
	v_cvt_pk_bf16_f32 v70, v72, v73
	v_cvt_pk_bf16_f32 v71, v74, v75
	v_cvt_pk_bf16_f32 v72, v76, v77
	s_waitcnt lgkmcnt(0)
	v_add_f32_e32 v68, v68, v69
	ds_bpermute_b32 v69, v120, v68
	v_cvt_pk_bf16_f32 v73, v78, v79
	global_store_dwordx4 v[98:99], v[70:73], off offset:256 sc1
	s_and_saveexec_b64 s[16:17], s[6:7]
	s_cbranch_execz .LBB0_1419
	s_waitcnt lgkmcnt(0)
	v_add_f32_e32 v70, v68, v69
	v_lshl_add_u64 v[68:69], v[84:85], 2, s[12:13]
	v_mov_b32_e32 v236, v68
	v_mov_b32_e32 v237, v69
	v_mov_b32_e32 v238, v70
; #define EPI_ROWS(...) _Pragma("unroll") for (int ai = 0; ai < 2; ++ai) _Pragma("unroll") for (int m = 0; m < 4; ++m) { const int row = row0 + ai * 128 + m * 16; __VA_ARGS__ __builtin_amdgcn_sched_barrier(0); }
; __device__ __forceinline__ u32x4 pack8(f32x4 a, f32x4 b) { u32x4 w; w.x = pk2(a[0], a[1]); w.y = pk2(a[2], a[3]); w.z = pk2(b[0], b[1]); w.w = pk2(b[2], b[3]); return w; }
; __device__ __forceinline__ float dot8(f32x4 a, f32x4 b) { return (a[0] * a[0] + a[1] * a[1]) + (a[2] * a[2] + a[3] * a[3]) + (b[0] * b[0] + b[1] * b[1]) + (b[2] * b[2] + b[3] * b[3]); }
; __device__ __forceinline__ float red_fq(float s) { s += __shfl_xor(s, 16); s += __shfl_xor(s, 32); return s; }
;     __device__ __forceinline__ void operator()(AccRef acc, const Unit& u, int wr, int wc, int fr, int fq) const {
;         const int row0 = u.pm * 256 + wr * 64 + fr, col0 = u.pn * 256 + wc * 32 + 8 * fq;
;         EPI_ROWS(
;             const float* rp = (row < MP) ? res0 + (size_t)row * DM : res1 + (size_t)(row - MP) * DM;
;             float s = 0.f;
;             _Pragma("unroll") for (int bj = 0; bj < 2; ++bj) { const int col = col0 + bj * 128;
;                 f32x4 v0 = *(const f32x4*)(rp + col) + acc[ai][bj][m][0] * scale, v1 = *(const f32x4*)(rp + col + 4) + acc[ai][bj][m][1] * scale;
;                 *(f32x4*)(out + (size_t)row * DM + col) = v0; *(f32x4*)(out + (size_t)row * DM + col + 4) = v1;
;                 if (WB) *(u32x4*)(ob + (size_t)row * DM + col) = pack8(v0, v1);
;                 s += dot8(v0, v1); }
;             s = red_fq(s); if (fq == 0) unsafeAtomicAdd(ss + row, s);
;         )
.LBB0_1419:
	s_or_b64 exec, exec, s[16:17]
	s_movk_i32 s16, 0x7f7f
	s_waitcnt lgkmcnt(0)
	v_add_u32_e32 v68, 0x80, v146
	v_cmp_lt_i32_e32 vcc, s16, v146
	s_and_saveexec_b64 s[16:17], vcc
	s_xor_b64 s[16:17], exec, s[16:17]
	v_add_u32_e32 v70, 0xffff8080, v146
	v_mov_b32_e32 v71, v2
	v_lshlrev_b64 v[70:71], 12, v[70:71]
	v_lshl_add_u64 v[70:71], s[10:11], 0, v[70:71]
	v_mov_b32_e32 v69, v2
	s_andn2_saveexec_b64 s[16:17], s[16:17]
	v_ashrrev_i32_e32 v69, 31, v68
	v_lshlrev_b64 v[70:71], 12, v[68:69]
	v_lshl_add_u64 v[70:71], s[30:31], 0, v[70:71]
	s_or_b64 exec, exec, s[16:17]
	v_lshl_add_u64 v[78:79], v[70:71], 0, v[144:145]
	global_load_dwordx4 v[70:73], v[78:79], off
	global_load_dwordx4 v[74:77], v[78:79], off offset:16
	global_load_dwordx4 v[216:219], v[78:79], off offset:512
	global_load_dwordx4 v[220:223], v[78:79], off offset:528
	v_lshlrev_b64 v[80:81], 12, v[68:69]
	v_lshlrev_b64 v[82:83], 11, v[68:69]
	v_lshl_add_u64 v[80:81], s[30:31], 0, v[80:81]
	v_lshl_add_u64 v[82:83], s[18:19], 0, v[82:83]
	v_lshl_add_u64 v[80:81], v[80:81], 0, v[144:145]
	v_lshl_add_u64 v[82:83], v[142:143], 1, v[82:83]
	s_waitcnt vmcnt(3)
	v_pk_add_f32 v[66:67], v[72:73], v[66:67]
	v_pk_add_f32 v[64:65], v[70:71], v[64:65]
	s_waitcnt vmcnt(2)
	v_pk_add_f32 v[62:63], v[76:77], v[62:63]
	v_pk_add_f32 v[60:61], v[74:75], v[60:61]
	v_cvt_pk_bf16_f32 v70, v64, v65
	v_cvt_pk_bf16_f32 v71, v66, v67
	v_cvt_pk_bf16_f32 v72, v60, v61
	v_cvt_pk_bf16_f32 v73, v62, v63
	global_store_dwordx4 v[80:81], v[64:67], off
	global_store_dwordx4 v[80:81], v[60:63], off offset:16
	global_store_dwordx4 v[82:83], v[70:73], off sc1
	s_nop 0
	s_nop 0
	s_nop 0
	v_mul_f32_e32 v65, v65, v65
	v_mul_f32_e32 v67, v67, v67
	v_mul_f32_e32 v61, v61, v61
	v_fmac_f32_e32 v65, v64, v64
	v_fmac_f32_e32 v67, v66, v66
	v_mul_f32_e32 v63, v63, v63
	v_fmac_f32_e32 v61, v60, v60
	v_add_f32_e32 v60, v65, v67
	v_fmac_f32_e32 v63, v62, v62
	v_add_f32_e32 v60, v61, v60
	v_add_f32_e32 v64, v63, v60
	s_waitcnt vmcnt(4)
	v_pk_add_f32 v[58:59], v[218:219], v[58:59]
	v_pk_add_f32 v[56:57], v[216:217], v[56:57]
	s_waitcnt vmcnt(3)
	v_pk_add_f32 v[60:61], v[220:221], v[52:53]
	v_mul_f32_e32 v52, v57, v57
	v_mul_f32_e32 v53, v59, v59
	v_pk_add_f32 v[62:63], v[222:223], v[54:55]
	v_mul_f32_e32 v54, v61, v61
	v_fmac_f32_e32 v52, v56, v56
	v_fmac_f32_e32 v53, v58, v58
	v_mul_f32_e32 v55, v63, v63
	v_fmac_f32_e32 v54, v60, v60
	v_add_f32_e32 v52, v52, v53
	v_add_f32_e32 v52, v54, v52
	v_fmac_f32_e32 v55, v62, v62
	v_add_f32_e32 v52, v55, v52
	v_add_f32_e32 v52, v64, v52
	ds_bpermute_b32 v53, v3, v52
	global_store_dwordx4 v[80:81], v[56:59], off offset:512
	global_store_dwordx4 v[80:81], v[60:63], off offset:528
	v_cvt_pk_bf16_f32 v54, v56, v57
	v_cvt_pk_bf16_f32 v55, v58, v59
	v_cvt_pk_bf16_f32 v56, v60, v61
	s_waitcnt lgkmcnt(0)
	v_add_f32_e32 v52, v52, v53
	ds_bpermute_b32 v53, v120, v52
	v_cvt_pk_bf16_f32 v57, v62, v63
	global_store_dwordx4 v[82:83], v[54:57], off offset:256 sc1
	s_and_saveexec_b64 s[16:17], s[6:7]
	s_cbranch_execz .LBB0_1425
	s_waitcnt lgkmcnt(0)
	v_add_f32_e32 v54, v52, v53
	v_lshl_add_u64 v[52:53], v[68:69], 2, s[12:13]
	v_mov_b32_e32 v240, v52
	v_mov_b32_e32 v241, v53
	v_mov_b32_e32 v242, v54
.LBB0_1425:
	s_or_b64 exec, exec, s[16:17]
	s_movk_i32 s16, 0x7f6f
	s_waitcnt lgkmcnt(0)
	v_add_u32_e32 v52, 0x90, v146
	v_cmp_lt_i32_e32 vcc, s16, v146
	s_and_saveexec_b64 s[16:17], vcc
	s_xor_b64 s[16:17], exec, s[16:17]
	v_add_u32_e32 v54, 0xffff8090, v146
	v_mov_b32_e32 v55, v2
	v_lshlrev_b64 v[54:55], 12, v[54:55]
	v_lshl_add_u64 v[54:55], s[10:11], 0, v[54:55]
	v_mov_b32_e32 v53, v2
	s_andn2_saveexec_b64 s[16:17], s[16:17]
	v_ashrrev_i32_e32 v53, 31, v52
	v_lshlrev_b64 v[54:55], 12, v[52:53]
	v_lshl_add_u64 v[54:55], s[30:31], 0, v[54:55]
	s_or_b64 exec, exec, s[16:17]
	v_lshl_add_u64 v[62:63], v[54:55], 0, v[144:145]
	global_load_dwordx4 v[54:57], v[62:63], off
	global_load_dwordx4 v[58:61], v[62:63], off offset:16
	global_load_dwordx4 v[216:219], v[62:63], off offset:512
	global_load_dwordx4 v[220:223], v[62:63], off offset:528
	v_lshlrev_b64 v[64:65], 12, v[52:53]
	v_lshlrev_b64 v[66:67], 11, v[52:53]
	v_lshl_add_u64 v[64:65], s[30:31], 0, v[64:65]
	v_lshl_add_u64 v[66:67], s[18:19], 0, v[66:67]
	v_lshl_add_u64 v[64:65], v[64:65], 0, v[144:145]
	v_lshl_add_u64 v[66:67], v[142:143], 1, v[66:67]
	s_waitcnt vmcnt(3)
	v_pk_add_f32 v[50:51], v[56:57], v[50:51]
	v_pk_add_f32 v[48:49], v[54:55], v[48:49]
	s_waitcnt vmcnt(2)
	v_pk_add_f32 v[46:47], v[60:61], v[46:47]
	v_pk_add_f32 v[44:45], v[58:59], v[44:45]
	v_cvt_pk_bf16_f32 v54, v48, v49
	v_cvt_pk_bf16_f32 v55, v50, v51
	v_cvt_pk_bf16_f32 v56, v44, v45
	v_cvt_pk_bf16_f32 v57, v46, v47
	global_store_dwordx4 v[64:65], v[48:51], off
	global_store_dwordx4 v[64:65], v[44:47], off offset:16
	global_store_dwordx4 v[66:67], v[54:57], off sc1
	s_nop 0
	s_nop 0
	s_nop 0
	v_mul_f32_e32 v49, v49, v49
	v_mul_f32_e32 v51, v51, v51
	v_mul_f32_e32 v45, v45, v45
	v_fmac_f32_e32 v49, v48, v48
	v_fmac_f32_e32 v51, v50, v50
	v_mul_f32_e32 v47, v47, v47
	v_fmac_f32_e32 v45, v44, v44
	v_add_f32_e32 v44, v49, v51
	v_fmac_f32_e32 v47, v46, v46
	v_add_f32_e32 v44, v45, v44
	v_add_f32_e32 v48, v47, v44
	s_waitcnt vmcnt(4)
	v_pk_add_f32 v[42:43], v[218:219], v[42:43]
	v_pk_add_f32 v[40:41], v[216:217], v[40:41]
	s_waitcnt vmcnt(3)
	v_pk_add_f32 v[44:45], v[220:221], v[36:37]
	v_mul_f32_e32 v36, v41, v41
	v_mul_f32_e32 v37, v43, v43
	v_pk_add_f32 v[46:47], v[222:223], v[38:39]
	v_mul_f32_e32 v38, v45, v45
	v_fmac_f32_e32 v36, v40, v40
	v_fmac_f32_e32 v37, v42, v42
	v_mul_f32_e32 v39, v47, v47
	v_fmac_f32_e32 v38, v44, v44
	v_add_f32_e32 v36, v36, v37
	v_add_f32_e32 v36, v38, v36
	v_fmac_f32_e32 v39, v46, v46
	v_add_f32_e32 v36, v39, v36
	v_add_f32_e32 v36, v48, v36
	ds_bpermute_b32 v37, v3, v36
	global_store_dwordx4 v[64:65], v[40:43], off offset:512
	global_store_dwordx4 v[64:65], v[44:47], off offset:528
	v_cvt_pk_bf16_f32 v38, v40, v41
	v_cvt_pk_bf16_f32 v39, v42, v43
	v_cvt_pk_bf16_f32 v40, v44, v45
	s_waitcnt lgkmcnt(0)
	v_add_f32_e32 v36, v36, v37
	ds_bpermute_b32 v37, v120, v36
	v_cvt_pk_bf16_f32 v41, v46, v47
	global_store_dwordx4 v[66:67], v[38:41], off offset:256 sc1
	s_and_saveexec_b64 s[16:17], s[6:7]
	s_cbranch_execz .LBB0_1431
	s_waitcnt lgkmcnt(0)
	v_add_f32_e32 v38, v36, v37
	v_lshl_add_u64 v[36:37], v[52:53], 2, s[12:13]
	v_mov_b32_e32 v244, v36
	v_mov_b32_e32 v245, v37
	v_mov_b32_e32 v246, v38
; #define EPI_ROWS(...) _Pragma("unroll") for (int ai = 0; ai < 2; ++ai) _Pragma("unroll") for (int m = 0; m < 4; ++m) { const int row = row0 + ai * 128 + m * 16; __VA_ARGS__ __builtin_amdgcn_sched_barrier(0); }
; __device__ __forceinline__ u32x4 pack8(f32x4 a, f32x4 b) { u32x4 w; w.x = pk2(a[0], a[1]); w.y = pk2(a[2], a[3]); w.z = pk2(b[0], b[1]); w.w = pk2(b[2], b[3]); return w; }
; __device__ __forceinline__ float dot8(f32x4 a, f32x4 b) { return (a[0] * a[0] + a[1] * a[1]) + (a[2] * a[2] + a[3] * a[3]) + (b[0] * b[0] + b[1] * b[1]) + (b[2] * b[2] + b[3] * b[3]); }
; __device__ __forceinline__ float red_fq(float s) { s += __shfl_xor(s, 16); s += __shfl_xor(s, 32); return s; }
;     __device__ __forceinline__ void operator()(AccRef acc, const Unit& u, int wr, int wc, int fr, int fq) const {
;         const int row0 = u.pm * 256 + wr * 64 + fr, col0 = u.pn * 256 + wc * 32 + 8 * fq;
;         EPI_ROWS(
;             const float* rp = (row < MP) ? res0 + (size_t)row * DM : res1 + (size_t)(row - MP) * DM;
;             float s = 0.f;
;             _Pragma("unroll") for (int bj = 0; bj < 2; ++bj) { const int col = col0 + bj * 128;
;                 f32x4 v0 = *(const f32x4*)(rp + col) + acc[ai][bj][m][0] * scale, v1 = *(const f32x4*)(rp + col + 4) + acc[ai][bj][m][1] * scale;
;                 *(f32x4*)(out + (size_t)row * DM + col) = v0; *(f32x4*)(out + (size_t)row * DM + col + 4) = v1;
;                 if (WB) *(u32x4*)(ob + (size_t)row * DM + col) = pack8(v0, v1);
;                 s += dot8(v0, v1); }
;             s = red_fq(s); if (fq == 0) unsafeAtomicAdd(ss + row, s);
;         )
.LBB0_1431:
	s_or_b64 exec, exec, s[16:17]
	s_movk_i32 s16, 0x7f5f
	s_waitcnt lgkmcnt(0)
	v_add_u32_e32 v36, 0xa0, v146
	v_cmp_lt_i32_e32 vcc, s16, v146
	s_and_saveexec_b64 s[16:17], vcc
	s_xor_b64 s[16:17], exec, s[16:17]
	v_add_u32_e32 v38, 0xffff80a0, v146
	v_mov_b32_e32 v39, v2
	v_lshlrev_b64 v[38:39], 12, v[38:39]
	v_lshl_add_u64 v[38:39], s[10:11], 0, v[38:39]
	v_mov_b32_e32 v37, v2
	s_andn2_saveexec_b64 s[16:17], s[16:17]
	v_ashrrev_i32_e32 v37, 31, v36
	v_lshlrev_b64 v[38:39], 12, v[36:37]
	v_lshl_add_u64 v[38:39], s[30:31], 0, v[38:39]
	s_or_b64 exec, exec, s[16:17]
	v_lshl_add_u64 v[46:47], v[38:39], 0, v[144:145]
	global_load_dwordx4 v[38:41], v[46:47], off
	global_load_dwordx4 v[42:45], v[46:47], off offset:16
	global_load_dwordx4 v[216:219], v[46:47], off offset:512
	global_load_dwordx4 v[220:223], v[46:47], off offset:528
	v_lshlrev_b64 v[48:49], 12, v[36:37]
	v_lshlrev_b64 v[50:51], 11, v[36:37]
	v_lshl_add_u64 v[48:49], s[30:31], 0, v[48:49]
	v_lshl_add_u64 v[50:51], s[18:19], 0, v[50:51]
	v_lshl_add_u64 v[48:49], v[48:49], 0, v[144:145]
	v_lshl_add_u64 v[50:51], v[142:143], 1, v[50:51]
	s_waitcnt vmcnt(3)
	v_pk_add_f32 v[34:35], v[40:41], v[34:35]
	v_pk_add_f32 v[32:33], v[38:39], v[32:33]
	s_waitcnt vmcnt(2)
	v_pk_add_f32 v[30:31], v[44:45], v[30:31]
	v_pk_add_f32 v[28:29], v[42:43], v[28:29]
	v_cvt_pk_bf16_f32 v38, v32, v33
	v_cvt_pk_bf16_f32 v39, v34, v35
	v_cvt_pk_bf16_f32 v40, v28, v29
	v_cvt_pk_bf16_f32 v41, v30, v31
	global_store_dwordx4 v[48:49], v[32:35], off
	global_store_dwordx4 v[48:49], v[28:31], off offset:16
	global_store_dwordx4 v[50:51], v[38:41], off sc1
	s_nop 0
	s_nop 0
	s_nop 0
	v_mul_f32_e32 v33, v33, v33
	v_mul_f32_e32 v35, v35, v35
	v_mul_f32_e32 v29, v29, v29
	v_fmac_f32_e32 v33, v32, v32
	v_fmac_f32_e32 v35, v34, v34
	v_mul_f32_e32 v31, v31, v31
	v_fmac_f32_e32 v29, v28, v28
	v_add_f32_e32 v28, v33, v35
	v_fmac_f32_e32 v31, v30, v30
	v_add_f32_e32 v28, v29, v28
	v_add_f32_e32 v32, v31, v28
	s_waitcnt vmcnt(4)
	v_pk_add_f32 v[26:27], v[218:219], v[26:27]
	v_pk_add_f32 v[24:25], v[216:217], v[24:25]
	s_waitcnt vmcnt(3)
	v_pk_add_f32 v[28:29], v[220:221], v[20:21]
	v_mul_f32_e32 v20, v25, v25
	v_mul_f32_e32 v21, v27, v27
	v_pk_add_f32 v[30:31], v[222:223], v[22:23]
	v_mul_f32_e32 v22, v29, v29
	v_fmac_f32_e32 v20, v24, v24
	v_fmac_f32_e32 v21, v26, v26
	v_mul_f32_e32 v23, v31, v31
	v_fmac_f32_e32 v22, v28, v28
	v_add_f32_e32 v20, v20, v21
	v_add_f32_e32 v20, v22, v20
	v_fmac_f32_e32 v23, v30, v30
	v_add_f32_e32 v20, v23, v20
	v_add_f32_e32 v20, v32, v20
	ds_bpermute_b32 v21, v3, v20
	global_store_dwordx4 v[48:49], v[24:27], off offset:512
	global_store_dwordx4 v[48:49], v[28:31], off offset:528
	v_cvt_pk_bf16_f32 v22, v24, v25
	v_cvt_pk_bf16_f32 v23, v26, v27
	v_cvt_pk_bf16_f32 v24, v28, v29
	s_waitcnt lgkmcnt(0)
	v_add_f32_e32 v20, v20, v21
	ds_bpermute_b32 v21, v120, v20
	v_cvt_pk_bf16_f32 v25, v30, v31
	global_store_dwordx4 v[50:51], v[22:25], off offset:256 sc1
	s_and_saveexec_b64 s[16:17], s[6:7]
	s_cbranch_execz .LBB0_1437
	s_waitcnt lgkmcnt(0)
	v_add_f32_e32 v22, v20, v21
	v_lshl_add_u64 v[20:21], v[36:37], 2, s[12:13]
	v_mov_b32_e32 v248, v20
	v_mov_b32_e32 v249, v21
	v_mov_b32_e32 v250, v22
.LBB0_1437:
	s_or_b64 exec, exec, s[16:17]
	s_movk_i32 s16, 0x7f4f
	s_waitcnt lgkmcnt(0)
	v_add_u32_e32 v20, 0xb0, v146
	v_cmp_lt_i32_e32 vcc, s16, v146
	s_and_saveexec_b64 s[16:17], vcc
	s_xor_b64 s[16:17], exec, s[16:17]
	v_add_u32_e32 v22, 0xffff80b0, v146
	v_mov_b32_e32 v23, v2
	v_lshlrev_b64 v[22:23], 12, v[22:23]
	v_lshl_add_u64 v[22:23], s[10:11], 0, v[22:23]
	v_mov_b32_e32 v21, v2
	s_andn2_saveexec_b64 s[16:17], s[16:17]
	v_ashrrev_i32_e32 v21, 31, v20
	v_lshlrev_b64 v[22:23], 12, v[20:21]
	v_lshl_add_u64 v[22:23], s[30:31], 0, v[22:23]
	s_or_b64 exec, exec, s[16:17]
	v_lshl_add_u64 v[30:31], v[22:23], 0, v[144:145]
	global_load_dwordx4 v[22:25], v[30:31], off
	global_load_dwordx4 v[26:29], v[30:31], off offset:16
	global_load_dwordx4 v[216:219], v[30:31], off offset:512
	global_load_dwordx4 v[220:223], v[30:31], off offset:528
	v_lshlrev_b64 v[32:33], 12, v[20:21]
	v_lshlrev_b64 v[34:35], 11, v[20:21]
	v_lshl_add_u64 v[32:33], s[30:31], 0, v[32:33]
	v_lshl_add_u64 v[34:35], s[18:19], 0, v[34:35]
	v_lshl_add_u64 v[32:33], v[32:33], 0, v[144:145]
	v_lshl_add_u64 v[34:35], v[142:143], 1, v[34:35]
	s_waitcnt vmcnt(3)
	v_pk_add_f32 v[18:19], v[24:25], v[18:19]
	v_pk_add_f32 v[16:17], v[22:23], v[16:17]
	s_waitcnt vmcnt(2)
	v_pk_add_f32 v[14:15], v[28:29], v[14:15]
	v_pk_add_f32 v[12:13], v[26:27], v[12:13]
	v_cvt_pk_bf16_f32 v22, v16, v17
	v_cvt_pk_bf16_f32 v23, v18, v19
	v_cvt_pk_bf16_f32 v24, v12, v13
	v_cvt_pk_bf16_f32 v25, v14, v15
	global_store_dwordx4 v[32:33], v[16:19], off
	global_store_dwordx4 v[32:33], v[12:15], off offset:16
	global_store_dwordx4 v[34:35], v[22:25], off sc1
	s_nop 0
	s_nop 0
	s_nop 0
	v_mul_f32_e32 v17, v17, v17
	v_mul_f32_e32 v19, v19, v19
	v_mul_f32_e32 v13, v13, v13
	v_fmac_f32_e32 v17, v16, v16
	v_fmac_f32_e32 v19, v18, v18
	v_mul_f32_e32 v15, v15, v15
	v_fmac_f32_e32 v13, v12, v12
	v_add_f32_e32 v12, v17, v19
	v_fmac_f32_e32 v15, v14, v14
	v_add_f32_e32 v12, v13, v12
	v_add_f32_e32 v16, v15, v12
	s_waitcnt vmcnt(4)
	v_pk_add_f32 v[10:11], v[218:219], v[10:11]
	v_pk_add_f32 v[8:9], v[216:217], v[8:9]
	s_waitcnt vmcnt(3)
	v_pk_add_f32 v[12:13], v[220:221], v[4:5]
	v_mul_f32_e32 v4, v9, v9
	v_mul_f32_e32 v5, v11, v11
	v_pk_add_f32 v[14:15], v[222:223], v[6:7]
	v_mul_f32_e32 v6, v13, v13
	v_fmac_f32_e32 v4, v8, v8
	v_fmac_f32_e32 v5, v10, v10
	v_mul_f32_e32 v7, v15, v15
	v_fmac_f32_e32 v6, v12, v12
	v_add_f32_e32 v4, v4, v5
	v_add_f32_e32 v4, v6, v4
	v_fmac_f32_e32 v7, v14, v14
	v_add_f32_e32 v4, v7, v4
	v_add_f32_e32 v4, v16, v4
	ds_bpermute_b32 v3, v3, v4
	global_store_dwordx4 v[32:33], v[8:11], off offset:512
	global_store_dwordx4 v[32:33], v[12:15], off offset:528
	v_cvt_pk_bf16_f32 v6, v8, v9
	v_cvt_pk_bf16_f32 v7, v10, v11
	v_cvt_pk_bf16_f32 v8, v12, v13
	s_waitcnt lgkmcnt(0)
	v_add_f32_e32 v3, v4, v3
	ds_bpermute_b32 v4, v120, v3
	v_cvt_pk_bf16_f32 v9, v14, v15
	global_store_dwordx4 v[34:35], v[6:9], off offset:256 sc1
	s_and_saveexec_b64 s[16:17], s[6:7]
	s_cbranch_execz .LBB0_1443
	s_waitcnt lgkmcnt(0)
	v_add_f32_e32 v3, v3, v4
	v_lshl_add_u64 v[4:5], v[20:21], 2, s[12:13]
	global_atomic_add_f32 v[4:5], v3, off
	global_atomic_add_f32 v[224:225], v226, off
	global_atomic_add_f32 v[228:229], v230, off
	global_atomic_add_f32 v[232:233], v234, off
	global_atomic_add_f32 v[236:237], v238, off
	global_atomic_add_f32 v[240:241], v242, off
	global_atomic_add_f32 v[244:245], v246, off
	global_atomic_add_f32 v[248:249], v250, off
